# GEMM K-loops: first two DMA waits of a unit's first iteration use vmcnt(8+S) so the previous epilogue's stores/atomics are not waited for (in-order vmcnt); with barrier edits + P2 plain
# speedup vs baseline: 1.0046x; 1.0046x over previous
; #define PG8_STAGE(bufoff, gbase, voff) do { _Pragma("unroll") for (int _i = 0; _i < 2; ++_i) \
;         __builtin_amdgcn_global_load_lds((const unsigned*)((const char*)(gbase) + (voff)[_i]), (PG8_LAS unsigned*)(lds + (bufoff) + ldsw + _i * 8192), 16, 0, 0); } while (0)
; #define PG8_WAIT_V(n) asm volatile("s_waitcnt vmcnt(" #n ")" ::: "memory")
; #define PG8_BAR __builtin_amdgcn_s_barrier()
; template <class Epi, class Sched, bool ALIGN_EPI = false, bool SP2 = false>
; __device__ __forceinline__ void gemm_phase(PG8_LAS unsigned char* lds, const Gemm g, const Sched& S, const Epi& E, volatile PG8_LAS unsigned* sw = nullptr) {
;     ...
;     const int tid = tid_, wid = __builtin_amdgcn_readfirstlane(tid >> 6), lane = tid & 63, wr = wid >> 2, wc = wid & 3, fr = lane & 15, fq = lane >> 4;
;     const int K = g.K, nt = K / BK;
;     unsigned voffA[2], voffB[2];
; #pragma unroll
;     for (int i = 0; i < 2; ++i) { int R, C; stage_rc(tid * 16 + i * 8192, R, C); const int Rb = Epi::PERM ? ((R & ~31) + perm32(R & 31)) : R;
;         const int Ra = Epi::PERMA ? ((R & 64) + 4 * (R & 15) + ((R >> 4) & 3)) : R;
;         voffA[i] = (unsigned)(Ra * BK + C) * 2u; voffB[i] = (unsigned)(Rb * BK + C) * 2u; }
;     const size_t kstep = (size_t)(BM * BK * 2);
;     const size_t hstep = (size_t)HALF * BK * 2;
;     const size_t tstep = (size_t)K * BM * 2;
;     const unsigned ldsw = (unsigned)wid * 1024u;
;     const int aoff = lds_byte(wr * 64 + fr, fq * 8), boff = lds_byte(wc * 32 + fr, fq * 8);
;     ...
;         PG8_WAIT_V(2); PG8_BAR;
;         PG8_STAGE(PG8_SB(1, 0), cB + kstep, voffB); PG8_STAGE(PG8_SA(1, 0), cA + kstep, voffA); PG8_STAGE(PG8_SB(1, 1), cB + hstep + kstep, voffB);
;         PG8_WAIT_V(6); PG8_BAR;
.LBB0_156:
	s_add_u32 s0, s50, 0x8000
	s_addc_u32 s1, s51, 0
	s_add_u32 s8, s48, 0x8000
	s_addc_u32 s9, s49, 0
	s_add_u32 s10, s50, 0xc000
	s_addc_u32 s11, s51, 0
	s_lshl_b32 s12, s61, 2
	s_add_u32 s33, s91, s12
	s_addc_u32 s40, s92, 0
	s_add_i32 m0, s20, 0x18000
	v_lshl_add_u64 v[10:11], s[0:1], 0, v[134:135]
	s_waitcnt vmcnt(2)
	s_barrier
	global_load_lds_dwordx4 v[10:11], off
	v_lshl_add_u64 v[10:11], s[0:1], 0, v[130:131]
	s_add_i32 m0, s20, 0x1a000
	s_add_i32 s41, s20, 0x8000
	global_load_lds_dwordx4 v[10:11], off
	v_lshl_add_u64 v[10:11], s[8:9], 0, v[136:137]
	s_mov_b32 m0, s41
	s_add_i32 s42, s20, 0xa000
	global_load_lds_dwordx4 v[10:11], off
	v_lshl_add_u64 v[10:11], s[8:9], 0, v[132:133]
	s_mov_b32 m0, s42
	v_and_b32_e32 v9, 15, v2
	global_load_lds_dwordx4 v[10:11], off
	s_add_i32 m0, s20, 0x1c000
	v_lshl_add_u64 v[10:11], s[10:11], 0, v[134:135]
	global_load_lds_dwordx4 v[10:11], off
	v_lshl_add_u64 v[10:11], s[10:11], 0, v[130:131]
	s_add_i32 m0, s20, 0x1e000
	s_and_b32 s0, s3, 3
	global_load_lds_dwordx4 v[10:11], off
	v_bfe_u32 v10, v2, 4, 2
	v_lshlrev_b32_e32 v12, 4, v10
	v_lshlrev_b32_e32 v2, 2, v2
	v_lshl_or_b32 v1, s7, 6, v9
	v_lshl_or_b32 v9, v9, 6, v12
	s_lshl_b32 s1, s7, 13
	v_and_b32_e32 v2, 32, v2
	v_bitop3_b32 v12, v9, s1, v2 bitop3:0xde
	s_lshl_b32 s1, s0, 12
	v_bitop3_b32 v144, v9, s1, v2 bitop3:0xde
	v_lshlrev_b32_e32 v2, 10, v7
	v_and_b32_e32 v2, 0xfffff800, v2
	v_lshl_add_u32 v2, v6, 7, v2
	v_and_b32_e32 v6, 1, v7
	v_lshl_or_b32 v2, v6, 6, v2
	v_lshl_add_u32 v138, v8, 1, v2
	v_lshlrev_b32_e32 v2, 10, v3
	v_and_b32_e32 v2, 0xfffff800, v2
	s_waitcnt vmcnt(6)
	s_cmpk_lt_u32 s6, 0x100
	v_lshl_add_u32 v2, v4, 7, v2
	v_and_b32_e32 v3, 1, v3
	v_lshlrev_b32_e32 v11, 3, v10
	s_cselect_b64 s[6:7], -1, 0
	v_lshl_or_b32 v2, v3, 6, v2
	s_add_i32 s57, 0, 0x10000
	s_add_i32 s58, 0, 0x14000
	s_mov_b32 s43, 0
	v_lshl_or_b32 v145, s0, 5, v11
	v_cmp_eq_u32_e64 s[0:1], 0, v10
	s_bfe_u32 s56, s3, 0x10001
	v_mov_b32_e32 v139, v135
	v_lshl_add_u32 v140, v5, 1, v2
	v_mov_b32_e32 v141, v135
	v_add_u32_e32 v146, s57, v144
	v_add_u32_e32 v147, s58, v144
	v_add_u32_e32 v148, 0, v12
	s_mov_b64 s[8:9], 0x100
	s_barrier
	s_mov_b32 s99, 0
	s_branch .LBB0_159

; template <class Epi, class Sched, bool ALIGN_EPI = false, bool SP2 = false>
; __device__ __forceinline__ void gemm_phase(PG8_LAS unsigned char* lds, const Gemm g, const Sched& S, const Epi& E, volatile PG8_LAS unsigned* sw = nullptr) {
;     ...
;         if (!has_next) break;
; #pragma unroll
;         for (int a = 0; a < 2; ++a)
; #pragma unroll
;             for (int b = 0; b < 2; ++b)
; #pragma unroll
;                 for (int m = 0; m < 4; ++m)
; #pragma unroll
;                     for (int n = 0; n < 2; ++n) acc[a][b][m][n] = (f32x4){0.f, 0.f, 0.f, 0.f};
;         cur = nxt; cA = nA; cB = nB; ++ui;
.LBB0_158:
	s_andn2_b64 vcc, exec, s[2:3]
	s_mov_b32 s2, s12
	s_mov_b32 s46, s10
	s_mov_b64 s[50:51], s[30:31]
	s_mov_b64 s[48:49], s[26:27]
	s_cbranch_vccz .LBB0_172
	s_mov_b32 s99, 1

; #define PG8_STAGE(bufoff, gbase, voff) do { _Pragma("unroll") for (int _i = 0; _i < 2; ++_i) \
;         __builtin_amdgcn_global_load_lds((const unsigned*)((const char*)(gbase) + (voff)[_i]), (PG8_LAS unsigned*)(lds + (bufoff) + ldsw + _i * 8192), 16, 0, 0); } while (0)
; #define PG8_LDA(dst, b, h) do { _Pragma("unroll") for (int m = 0; m < 4; ++m) _Pragma("unroll") for (int k = 0; k < 2; ++k) dst[m][k] = *(const PG8_LAS bf16x8*)(lds + PG8_SA(b, h) + aoff + m * 2048 + k * 1024); } while (0)
; #define PG8_LDB(dst, b, h) do { _Pragma("unroll") for (int n = 0; n < 2; ++n) _Pragma("unroll") for (int k = 0; k < 2; ++k) dst[n][k] = *(const PG8_LAS bf16x8*)(lds + PG8_SB(b, h) + boff + n * 2048 + k * 1024); } while (0)
; #define PG8_MMA(ai, bj, At, Bt) do { __builtin_amdgcn_s_setprio(1); _Pragma("unroll") for (int m = 0; m < 4; ++m) _Pragma("unroll") for (int n = 0; n < 2; ++n) _Pragma("unroll") for (int k = 0; k < 2; ++k) \
;         acc[ai][bj][m][n] = __builtin_amdgcn_mfma_f32_16x16x32_bf16(Bt[n][k], At[m][k], acc[ai][bj][m][n], 0, 0, 0); __builtin_amdgcn_s_setprio(0); } while (0)
; #define PG8_WAIT_V(n) asm volatile("s_waitcnt vmcnt(" #n ")" ::: "memory")
; #define PG8_WAIT_L(n) asm volatile("s_waitcnt lgkmcnt(" #n ")" ::: "memory")
; #define PG8_BAR __builtin_amdgcn_s_barrier()
; #define PG8_SCHED __builtin_amdgcn_sched_barrier(0)
; template <class Epi, class Sched, bool ALIGN_EPI = false, bool SP2 = false>
; __device__ __forceinline__ void gemm_phase(PG8_LAS unsigned char* lds, const Gemm g, const Sched& S, const Epi& E, volatile PG8_LAS unsigned* sw = nullptr) {
;     ...
;             PG8_LDB(B0, 0, 0); PG8_LDB(B1, 0, 1); PG8_SCHED; PG8_LDA(At, 0, 0); PG8_STAGE(PG8_SA(1, 1), a1 + hstep, voffA);
;             PG8_WAIT_V(8); PG8_WAIT_L(0); PG8_BAR; PG8_MMA(0, 0, At, B0); PG8_MMA(0, 1, At, B1); PG8_BAR; PG8_SCHED;
;             PG8_LDA(At, 0, 1); PG8_STAGE(PG8_SB(0, 0), b2, voffB); PG8_STAGE(PG8_SB(0, 1), b2 + hstep, voffB); PG8_STAGE(PG8_SA(0, 0), a2, voffA);
;             PG8_WAIT_V(8); PG8_WAIT_L(0); PG8_BAR; PG8_MMA(1, 0, At, B0); PG8_MMA(1, 1, At, B1); PG8_BAR; PG8_SCHED;
.LBB0_162:
	ds_read_b128 v[150:153], v146
	ds_read_b128 v[154:157], v146 offset:1024
	ds_read_b128 v[158:161], v146 offset:2048
	ds_read_b128 v[162:165], v146 offset:3072
	ds_read_b128 v[166:169], v147
	ds_read_b128 v[170:173], v147 offset:1024
	ds_read_b128 v[174:177], v147 offset:2048
	ds_read_b128 v[178:181], v147 offset:3072
	s_add_u32 s50, s48, 0x4000
	s_addc_u32 s51, s49, 0
	s_cmp_eq_u32 s65, 12
	s_cselect_b32 s54, s11, s50
	s_cselect_b32 s55, s3, s51
	s_cselect_b32 s52, s47, s59
	s_cselect_b32 s53, s13, s64
	s_add_u32 s50, s54, 0x8000
	s_addc_u32 s51, s55, 0
	v_lshl_add_u64 v[142:143], s[48:49], 0, v[138:139]
	s_add_i32 m0, s20, 0xc000
	ds_read_b128 v[182:185], v148
	ds_read_b128 v[186:189], v148 offset:1024
	ds_read_b128 v[190:193], v148 offset:2048
	ds_read_b128 v[194:197], v148 offset:3072
	ds_read_b128 v[198:201], v148 offset:4096
	ds_read_b128 v[202:205], v148 offset:5120
	ds_read_b128 v[206:209], v148 offset:6144
	ds_read_b128 v[210:213], v148 offset:7168
	global_load_lds_dwordx4 v[142:143], off
	v_lshl_add_u64 v[142:143], s[48:49], 0, v[140:141]
	s_add_i32 m0, s20, 0xe000
	s_nop 0
	global_load_lds_dwordx4 v[142:143], off
	s_cmp_lg_u32 s99, 0
	s_cbranch_scc1 .Lrx_p2_0_r
	s_waitcnt vmcnt(8)
	s_branch .Lrx_p2_0_j
.Lrx_p2_0_r:
	s_waitcnt vmcnt(24)
.Lrx_p2_0_j:
	s_waitcnt lgkmcnt(0)
	s_barrier
	s_setprio 1
	s_waitcnt lgkmcnt(0)
	v_mfma_f32_16x16x32_bf16 v[126:129], v[150:153], v[182:185], v[126:129]
	v_mfma_f32_16x16x32_bf16 v[122:125], v[158:161], v[182:185], v[122:125]
	v_mfma_f32_16x16x32_bf16 v[118:121], v[150:153], v[190:193], v[118:121]
	v_mfma_f32_16x16x32_bf16 v[110:113], v[158:161], v[190:193], v[110:113]
	v_mfma_f32_16x16x32_bf16 v[102:105], v[150:153], v[198:201], v[102:105]
	v_mfma_f32_16x16x32_bf16 v[94:97], v[158:161], v[198:201], v[94:97]
	v_mfma_f32_16x16x32_bf16 v[86:89], v[150:153], v[206:209], v[86:89]
	v_mfma_f32_16x16x32_bf16 v[78:81], v[158:161], v[206:209], v[78:81]
	v_mfma_f32_16x16x32_bf16 v[126:129], v[154:157], v[186:189], v[126:129]
	v_mfma_f32_16x16x32_bf16 v[122:125], v[162:165], v[186:189], v[122:125]
	v_mfma_f32_16x16x32_bf16 v[118:121], v[154:157], v[194:197], v[118:121]
	v_mfma_f32_16x16x32_bf16 v[110:113], v[162:165], v[194:197], v[110:113]
	v_mfma_f32_16x16x32_bf16 v[102:105], v[154:157], v[202:205], v[102:105]
	v_mfma_f32_16x16x32_bf16 v[94:97], v[162:165], v[202:205], v[94:97]
	v_mfma_f32_16x16x32_bf16 v[86:89], v[154:157], v[210:213], v[86:89]
	v_mfma_f32_16x16x32_bf16 v[78:81], v[162:165], v[210:213], v[78:81]
	s_setprio 0
	s_setprio 1
	v_mfma_f32_16x16x32_bf16 v[114:117], v[166:169], v[182:185], v[114:117]
	v_mfma_f32_16x16x32_bf16 v[106:109], v[174:177], v[182:185], v[106:109]
	v_mfma_f32_16x16x32_bf16 v[98:101], v[166:169], v[190:193], v[98:101]
	v_mfma_f32_16x16x32_bf16 v[90:93], v[174:177], v[190:193], v[90:93]
	v_mfma_f32_16x16x32_bf16 v[82:85], v[166:169], v[198:201], v[82:85]
	v_mfma_f32_16x16x32_bf16 v[74:77], v[174:177], v[198:201], v[74:77]
	v_mfma_f32_16x16x32_bf16 v[70:73], v[166:169], v[206:209], v[70:73]
	v_mfma_f32_16x16x32_bf16 v[66:69], v[174:177], v[206:209], v[66:69]
	v_mfma_f32_16x16x32_bf16 v[114:117], v[170:173], v[186:189], v[114:117]
	v_mfma_f32_16x16x32_bf16 v[106:109], v[178:181], v[186:189], v[106:109]
	v_mfma_f32_16x16x32_bf16 v[98:101], v[170:173], v[194:197], v[98:101]
	v_mfma_f32_16x16x32_bf16 v[90:93], v[178:181], v[194:197], v[90:93]
	v_mfma_f32_16x16x32_bf16 v[82:85], v[170:173], v[202:205], v[82:85]
	v_mfma_f32_16x16x32_bf16 v[74:77], v[178:181], v[202:205], v[74:77]
	v_mfma_f32_16x16x32_bf16 v[70:73], v[170:173], v[210:213], v[70:73]
	v_mfma_f32_16x16x32_bf16 v[66:69], v[178:181], v[210:213], v[66:69]
	s_setprio 0
	s_barrier
	s_add_i32 s70, s57, s19
	v_lshl_add_u64 v[142:143], s[52:53], 0, v[134:135]
	s_mov_b32 m0, s70
	ds_read_b128 v[182:185], v148 offset:16384
	ds_read_b128 v[186:189], v148 offset:17408
	ds_read_b128 v[190:193], v148 offset:18432
	ds_read_b128 v[194:197], v148 offset:19456
	ds_read_b128 v[198:201], v148 offset:20480
	ds_read_b128 v[202:205], v148 offset:21504
	ds_read_b128 v[206:209], v148 offset:22528
	ds_read_b128 v[210:213], v148 offset:23552
	global_load_lds_dwordx4 v[142:143], off
	s_add_i32 m0, s70, 0x2000
	s_add_u32 s70, s52, 0x4000
	v_lshl_add_u64 v[142:143], s[52:53], 0, v[130:131]
	s_addc_u32 s71, s53, 0
	s_add_i32 s72, s58, s19
	global_load_lds_dwordx4 v[142:143], off
	v_lshl_add_u64 v[142:143], s[70:71], 0, v[134:135]
	s_mov_b32 m0, s72
	s_nop 0
	global_load_lds_dwordx4 v[142:143], off
	v_lshl_add_u64 v[142:143], s[70:71], 0, v[130:131]
	s_add_i32 m0, s72, 0x2000
	s_nop 0
	global_load_lds_dwordx4 v[142:143], off
	v_lshl_add_u64 v[142:143], s[54:55], 0, v[136:137]
	s_mov_b32 m0, s20
	s_nop 0
	global_load_lds_dwordx4 v[142:143], off
	v_lshl_add_u64 v[142:143], s[54:55], 0, v[132:133]
	s_mov_b32 m0, s21
	s_nop 0
	global_load_lds_dwordx4 v[142:143], off
	s_cmp_lg_u32 s99, 0
	s_cbranch_scc1 .Lrx_p2_1_r
	s_waitcnt vmcnt(8)
	s_branch .Lrx_p2_1_j

; #define PG8_STAGE(bufoff, gbase, voff) do { _Pragma("unroll") for (int _i = 0; _i < 2; ++_i) \
;         __builtin_amdgcn_global_load_lds((const unsigned*)((const char*)(gbase) + (voff)[_i]), (PG8_LAS unsigned*)(lds + (bufoff) + ldsw + _i * 8192), 16, 0, 0); } while (0)
; #define PG8_LDA(dst, b, h) do { _Pragma("unroll") for (int m = 0; m < 4; ++m) _Pragma("unroll") for (int k = 0; k < 2; ++k) dst[m][k] = *(const PG8_LAS bf16x8*)(lds + PG8_SA(b, h) + aoff + m * 2048 + k * 1024); } while (0)
; #define PG8_LDB(dst, b, h) do { _Pragma("unroll") for (int n = 0; n < 2; ++n) _Pragma("unroll") for (int k = 0; k < 2; ++k) dst[n][k] = *(const PG8_LAS bf16x8*)(lds + PG8_SB(b, h) + boff + n * 2048 + k * 1024); } while (0)
; #define PG8_MMA(ai, bj, At, Bt) do { __builtin_amdgcn_s_setprio(1); _Pragma("unroll") for (int m = 0; m < 4; ++m) _Pragma("unroll") for (int n = 0; n < 2; ++n) _Pragma("unroll") for (int k = 0; k < 2; ++k) \
;         acc[ai][bj][m][n] = __builtin_amdgcn_mfma_f32_16x16x32_bf16(Bt[n][k], At[m][k], acc[ai][bj][m][n], 0, 0, 0); __builtin_amdgcn_s_setprio(0); } while (0)
; #define PG8_WAIT_V(n) asm volatile("s_waitcnt vmcnt(" #n ")" ::: "memory")
; #define PG8_WAIT_L(n) asm volatile("s_waitcnt lgkmcnt(" #n ")" ::: "memory")
; #define PG8_BAR __builtin_amdgcn_s_barrier()
; #define PG8_SCHED __builtin_amdgcn_sched_barrier(0)
; template <class Epi, class Sched, bool ALIGN_EPI = false, bool SP2 = false>
; __device__ __forceinline__ void gemm_phase(PG8_LAS unsigned char* lds, const Gemm g, const Sched& S, const Epi& E, volatile PG8_LAS unsigned* sw = nullptr) {
;     ...
;             PG8_WAIT_V(8); PG8_WAIT_L(0); PG8_BAR; PG8_MMA(1, 0, At, B0); PG8_MMA(1, 1, At, B1); PG8_BAR; PG8_SCHED;
;             PG8_LDB(B0, 1, 0); PG8_LDB(B1, 1, 1); PG8_SCHED; PG8_LDA(At, 1, 0); PG8_STAGE(PG8_SA(0, 1), a2 + hstep, voffA);
;             PG8_WAIT_V(8); PG8_WAIT_L(0); PG8_BAR; PG8_MMA(0, 0, At, B0); PG8_MMA(0, 1, At, B1); PG8_BAR; PG8_SCHED;
.Lrx_p2_1_j:
	s_mov_b32 s99, 0
	s_waitcnt lgkmcnt(0)
	s_barrier
	s_setprio 1
	s_waitcnt lgkmcnt(0)
	v_mfma_f32_16x16x32_bf16 v[62:65], v[150:153], v[182:185], v[62:65]
	v_mfma_f32_16x16x32_bf16 v[58:61], v[158:161], v[182:185], v[58:61]
	v_mfma_f32_16x16x32_bf16 v[54:57], v[150:153], v[190:193], v[54:57]
	v_mfma_f32_16x16x32_bf16 v[46:49], v[158:161], v[190:193], v[46:49]
	v_mfma_f32_16x16x32_bf16 v[38:41], v[150:153], v[198:201], v[38:41]
	v_mfma_f32_16x16x32_bf16 v[30:33], v[158:161], v[198:201], v[30:33]
	v_mfma_f32_16x16x32_bf16 v[22:25], v[150:153], v[206:209], v[22:25]
	v_mfma_f32_16x16x32_bf16 v[14:17], v[158:161], v[206:209], v[14:17]
	v_mfma_f32_16x16x32_bf16 v[62:65], v[154:157], v[186:189], v[62:65]
	v_mfma_f32_16x16x32_bf16 v[58:61], v[162:165], v[186:189], v[58:61]
	v_mfma_f32_16x16x32_bf16 v[54:57], v[154:157], v[194:197], v[54:57]
	v_mfma_f32_16x16x32_bf16 v[46:49], v[162:165], v[194:197], v[46:49]
	v_mfma_f32_16x16x32_bf16 v[38:41], v[154:157], v[202:205], v[38:41]
	v_mfma_f32_16x16x32_bf16 v[30:33], v[162:165], v[202:205], v[30:33]
	v_mfma_f32_16x16x32_bf16 v[22:25], v[154:157], v[210:213], v[22:25]
	v_mfma_f32_16x16x32_bf16 v[14:17], v[162:165], v[210:213], v[14:17]
	s_setprio 0
	s_setprio 1
	v_mfma_f32_16x16x32_bf16 v[50:53], v[166:169], v[182:185], v[50:53]
	v_mfma_f32_16x16x32_bf16 v[42:45], v[174:177], v[182:185], v[42:45]
	v_mfma_f32_16x16x32_bf16 v[34:37], v[166:169], v[190:193], v[34:37]
	v_mfma_f32_16x16x32_bf16 v[26:29], v[174:177], v[190:193], v[26:29]
	v_mfma_f32_16x16x32_bf16 v[18:21], v[166:169], v[198:201], v[18:21]
	v_mfma_f32_16x16x32_bf16 v[10:13], v[174:177], v[198:201], v[10:13]
	v_mfma_f32_16x16x32_bf16 v[6:9], v[166:169], v[206:209], v[6:9]
	v_mfma_f32_16x16x32_bf16 v[2:5], v[174:177], v[206:209], v[2:5]
	v_mfma_f32_16x16x32_bf16 v[50:53], v[170:173], v[186:189], v[50:53]
	v_mfma_f32_16x16x32_bf16 v[42:45], v[178:181], v[186:189], v[42:45]
	v_mfma_f32_16x16x32_bf16 v[34:37], v[170:173], v[194:197], v[34:37]
	v_mfma_f32_16x16x32_bf16 v[26:29], v[178:181], v[194:197], v[26:29]
	v_mfma_f32_16x16x32_bf16 v[18:21], v[170:173], v[202:205], v[18:21]
	v_mfma_f32_16x16x32_bf16 v[10:13], v[178:181], v[202:205], v[10:13]
	v_mfma_f32_16x16x32_bf16 v[6:9], v[170:173], v[210:213], v[6:9]
	v_mfma_f32_16x16x32_bf16 v[2:5], v[178:181], v[210:213], v[2:5]
	s_setprio 0
	s_barrier
	s_add_i32 s70, 0, 0x18000
	v_add_u32_e32 v142, s70, v144
	s_add_i32 s71, 0, 0x1c000
	ds_read_b128 v[150:153], v142
	ds_read_b128 v[154:157], v142 offset:1024
	ds_read_b128 v[158:161], v142 offset:2048
	ds_read_b128 v[162:165], v142 offset:3072
	v_add_u32_e32 v142, s71, v144
	ds_read_b128 v[166:169], v142
	ds_read_b128 v[170:173], v142 offset:1024
	ds_read_b128 v[174:177], v142 offset:2048
	ds_read_b128 v[178:181], v142 offset:3072
	s_add_u32 s54, s54, 0x4000
	s_addc_u32 s55, s55, 0
	s_mov_b32 m0, s22
	v_lshl_add_u64 v[142:143], s[54:55], 0, v[136:137]
	ds_read_b128 v[182:185], v148 offset:32768
	ds_read_b128 v[186:189], v148 offset:33792
	ds_read_b128 v[190:193], v148 offset:34816
	ds_read_b128 v[194:197], v148 offset:35840
	ds_read_b128 v[198:201], v148 offset:36864
	ds_read_b128 v[202:205], v148 offset:37888
	ds_read_b128 v[206:209], v148 offset:38912
	ds_read_b128 v[210:213], v148 offset:39936
	global_load_lds_dwordx4 v[142:143], off
	v_lshl_add_u64 v[142:143], s[54:55], 0, v[132:133]
	s_mov_b32 m0, s23
	s_nop 0
	global_load_lds_dwordx4 v[142:143], off
	s_waitcnt vmcnt(8)
	s_waitcnt lgkmcnt(0)
	s_barrier
	s_setprio 1
	s_waitcnt lgkmcnt(0)
	v_mfma_f32_16x16x32_bf16 v[126:129], v[150:153], v[182:185], v[126:129]
	v_mfma_f32_16x16x32_bf16 v[122:125], v[158:161], v[182:185], v[122:125]
	v_mfma_f32_16x16x32_bf16 v[118:121], v[150:153], v[190:193], v[118:121]
	v_mfma_f32_16x16x32_bf16 v[110:113], v[158:161], v[190:193], v[110:113]
	v_mfma_f32_16x16x32_bf16 v[102:105], v[150:153], v[198:201], v[102:105]
	v_mfma_f32_16x16x32_bf16 v[94:97], v[158:161], v[198:201], v[94:97]
	v_mfma_f32_16x16x32_bf16 v[86:89], v[150:153], v[206:209], v[86:89]
	v_mfma_f32_16x16x32_bf16 v[78:81], v[158:161], v[206:209], v[78:81]
	v_mfma_f32_16x16x32_bf16 v[126:129], v[154:157], v[186:189], v[126:129]
	v_mfma_f32_16x16x32_bf16 v[122:125], v[162:165], v[186:189], v[122:125]
	v_mfma_f32_16x16x32_bf16 v[118:121], v[154:157], v[194:197], v[118:121]
	v_mfma_f32_16x16x32_bf16 v[110:113], v[162:165], v[194:197], v[110:113]
	v_mfma_f32_16x16x32_bf16 v[102:105], v[154:157], v[202:205], v[102:105]
	v_mfma_f32_16x16x32_bf16 v[94:97], v[162:165], v[202:205], v[94:97]
	v_mfma_f32_16x16x32_bf16 v[86:89], v[154:157], v[210:213], v[86:89]
	v_mfma_f32_16x16x32_bf16 v[78:81], v[162:165], v[210:213], v[78:81]
	s_setprio 0
	s_setprio 1
	v_mfma_f32_16x16x32_bf16 v[114:117], v[166:169], v[182:185], v[114:117]
	v_mfma_f32_16x16x32_bf16 v[106:109], v[174:177], v[182:185], v[106:109]
	v_mfma_f32_16x16x32_bf16 v[98:101], v[166:169], v[190:193], v[98:101]
	v_mfma_f32_16x16x32_bf16 v[90:93], v[174:177], v[190:193], v[90:93]
	v_mfma_f32_16x16x32_bf16 v[82:85], v[166:169], v[198:201], v[82:85]
	v_mfma_f32_16x16x32_bf16 v[74:77], v[174:177], v[198:201], v[74:77]
	v_mfma_f32_16x16x32_bf16 v[70:73], v[166:169], v[206:209], v[70:73]
	v_mfma_f32_16x16x32_bf16 v[66:69], v[174:177], v[206:209], v[66:69]
	v_mfma_f32_16x16x32_bf16 v[114:117], v[170:173], v[186:189], v[114:117]
	v_mfma_f32_16x16x32_bf16 v[106:109], v[178:181], v[186:189], v[106:109]
	v_mfma_f32_16x16x32_bf16 v[98:101], v[170:173], v[194:197], v[98:101]
	v_mfma_f32_16x16x32_bf16 v[90:93], v[178:181], v[194:197], v[90:93]
	v_mfma_f32_16x16x32_bf16 v[82:85], v[170:173], v[202:205], v[82:85]
	v_mfma_f32_16x16x32_bf16 v[74:77], v[178:181], v[202:205], v[74:77]
	v_mfma_f32_16x16x32_bf16 v[70:73], v[170:173], v[210:213], v[70:73]
	v_mfma_f32_16x16x32_bf16 v[66:69], v[178:181], v[210:213], v[66:69]
	s_setprio 0
	s_barrier
; #define PG8_STAGE(bufoff, gbase, voff) do { _Pragma("unroll") for (int _i = 0; _i < 2; ++_i) \
;         __builtin_amdgcn_global_load_lds((const unsigned*)((const char*)(gbase) + (voff)[_i]), (PG8_LAS unsigned*)(lds + (bufoff) + ldsw + _i * 8192), 16, 0, 0); } while (0)
; #define PG8_LDA(dst, b, h) do { _Pragma("unroll") for (int m = 0; m < 4; ++m) _Pragma("unroll") for (int k = 0; k < 2; ++k) dst[m][k] = *(const PG8_LAS bf16x8*)(lds + PG8_SA(b, h) + aoff + m * 2048 + k * 1024); } while (0)
; #define PG8_MMA(ai, bj, At, Bt) do { __builtin_amdgcn_s_setprio(1); _Pragma("unroll") for (int m = 0; m < 4; ++m) _Pragma("unroll") for (int n = 0; n < 2; ++n) _Pragma("unroll") for (int k = 0; k < 2; ++k) \
;         acc[ai][bj][m][n] = __builtin_amdgcn_mfma_f32_16x16x32_bf16(Bt[n][k], At[m][k], acc[ai][bj][m][n], 0, 0, 0); __builtin_amdgcn_s_setprio(0); } while (0)
; #define PG8_WAIT_V(n) asm volatile("s_waitcnt vmcnt(" #n ")" ::: "memory")
; #define PG8_WAIT_L(n) asm volatile("s_waitcnt lgkmcnt(" #n ")" ::: "memory")
; #define PG8_BAR __builtin_amdgcn_s_barrier()
; #define PG8_SCHED __builtin_amdgcn_sched_barrier(0)
; template <class Epi, class Sched, bool ALIGN_EPI = false, bool SP2 = false>
; __device__ __forceinline__ void gemm_phase(PG8_LAS unsigned char* lds, const Gemm g, const Sched& S, const Epi& E, volatile PG8_LAS unsigned* sw = nullptr) {
;     ...
;             PG8_LDA(At, 1, 1); PG8_STAGE(PG8_SB(1, 0), b3, voffB); PG8_STAGE(PG8_SB(1, 1), b3 + hstep, voffB); PG8_STAGE(PG8_SA(1, 0), a3, voffA);
;             PG8_WAIT_V(8); PG8_WAIT_L(0); PG8_BAR; PG8_MMA(1, 0, At, B0); PG8_MMA(1, 1, At, B1); PG8_BAR; PG8_SCHED;
;     ...
;         if constexpr (ALIGN_EPI) { if (wr == 0) PG8_BAR; }
	s_add_u32 s54, s52, 0x8000
	s_addc_u32 s55, s53, 0
	s_add_i32 s70, s70, s19
	v_lshl_add_u64 v[142:143], s[54:55], 0, v[134:135]
	s_mov_b32 m0, s70
	ds_read_b128 v[182:185], v148 offset:49152
	ds_read_b128 v[186:189], v148 offset:50176
	ds_read_b128 v[190:193], v148 offset:51200
	ds_read_b128 v[194:197], v148 offset:52224
	ds_read_b128 v[198:201], v148 offset:53248
	ds_read_b128 v[202:205], v148 offset:54272
	ds_read_b128 v[206:209], v148 offset:55296
	ds_read_b128 v[210:213], v148 offset:56320
	global_load_lds_dwordx4 v[142:143], off
	s_add_i32 m0, s70, 0x2000
	s_add_u32 s52, s52, 0xc000
	v_lshl_add_u64 v[142:143], s[54:55], 0, v[130:131]
	s_addc_u32 s53, s53, 0
	s_add_i32 s54, s71, s19
	global_load_lds_dwordx4 v[142:143], off
	v_lshl_add_u64 v[142:143], s[52:53], 0, v[134:135]
	s_mov_b32 m0, s54
	s_nop 0
	global_load_lds_dwordx4 v[142:143], off
	v_lshl_add_u64 v[142:143], s[52:53], 0, v[130:131]
	s_add_i32 m0, s54, 0x2000
	s_nop 0
	global_load_lds_dwordx4 v[142:143], off
	v_lshl_add_u64 v[142:143], s[50:51], 0, v[136:137]
	s_mov_b32 m0, s41
	s_nop 0
	global_load_lds_dwordx4 v[142:143], off
	v_lshl_add_u64 v[142:143], s[50:51], 0, v[132:133]
	s_mov_b32 m0, s42
	s_nop 0
	global_load_lds_dwordx4 v[142:143], off
	s_waitcnt vmcnt(8)
	s_waitcnt lgkmcnt(0)
	s_barrier
	s_setprio 1
	s_waitcnt lgkmcnt(0)
	v_mfma_f32_16x16x32_bf16 v[62:65], v[150:153], v[182:185], v[62:65]
	v_mfma_f32_16x16x32_bf16 v[58:61], v[158:161], v[182:185], v[58:61]
	v_mfma_f32_16x16x32_bf16 v[54:57], v[150:153], v[190:193], v[54:57]
	v_mfma_f32_16x16x32_bf16 v[46:49], v[158:161], v[190:193], v[46:49]
	v_mfma_f32_16x16x32_bf16 v[38:41], v[150:153], v[198:201], v[38:41]
	v_mfma_f32_16x16x32_bf16 v[30:33], v[158:161], v[198:201], v[30:33]
	v_mfma_f32_16x16x32_bf16 v[22:25], v[150:153], v[206:209], v[22:25]
	v_mfma_f32_16x16x32_bf16 v[14:17], v[158:161], v[206:209], v[14:17]
	v_mfma_f32_16x16x32_bf16 v[62:65], v[154:157], v[186:189], v[62:65]
	v_mfma_f32_16x16x32_bf16 v[58:61], v[162:165], v[186:189], v[58:61]
	v_mfma_f32_16x16x32_bf16 v[54:57], v[154:157], v[194:197], v[54:57]
	v_mfma_f32_16x16x32_bf16 v[46:49], v[162:165], v[194:197], v[46:49]
	v_mfma_f32_16x16x32_bf16 v[38:41], v[154:157], v[202:205], v[38:41]
	v_mfma_f32_16x16x32_bf16 v[30:33], v[162:165], v[202:205], v[30:33]
	v_mfma_f32_16x16x32_bf16 v[22:25], v[154:157], v[210:213], v[22:25]
	v_mfma_f32_16x16x32_bf16 v[14:17], v[162:165], v[210:213], v[14:17]
	s_setprio 0
	s_setprio 1
	v_mfma_f32_16x16x32_bf16 v[50:53], v[166:169], v[182:185], v[50:53]
	v_mfma_f32_16x16x32_bf16 v[42:45], v[174:177], v[182:185], v[42:45]
	v_mfma_f32_16x16x32_bf16 v[34:37], v[166:169], v[190:193], v[34:37]
	v_mfma_f32_16x16x32_bf16 v[26:29], v[174:177], v[190:193], v[26:29]
	v_mfma_f32_16x16x32_bf16 v[18:21], v[166:169], v[198:201], v[18:21]
	v_mfma_f32_16x16x32_bf16 v[10:13], v[174:177], v[198:201], v[10:13]
	v_mfma_f32_16x16x32_bf16 v[6:9], v[166:169], v[206:209], v[6:9]
	v_mfma_f32_16x16x32_bf16 v[2:5], v[174:177], v[206:209], v[2:5]
	v_mfma_f32_16x16x32_bf16 v[50:53], v[170:173], v[186:189], v[50:53]
	v_mfma_f32_16x16x32_bf16 v[42:45], v[178:181], v[186:189], v[42:45]
	v_mfma_f32_16x16x32_bf16 v[34:37], v[170:173], v[194:197], v[34:37]
	v_mfma_f32_16x16x32_bf16 v[26:29], v[178:181], v[194:197], v[26:29]
	v_mfma_f32_16x16x32_bf16 v[18:21], v[170:173], v[202:205], v[18:21]
	v_mfma_f32_16x16x32_bf16 v[10:13], v[178:181], v[202:205], v[10:13]
	v_mfma_f32_16x16x32_bf16 v[6:9], v[170:173], v[210:213], v[6:9]
	v_mfma_f32_16x16x32_bf16 v[2:5], v[178:181], v[210:213], v[2:5]
	s_setprio 0
	s_barrier
	s_add_i32 s65, s65, 2
	s_add_u32 s48, s48, 0x10000
	s_addc_u32 s49, s49, 0
	s_add_u32 s59, s59, 0x10000
	s_addc_u32 s64, s64, 0
	s_cmp_gt_u32 s65, 13
	s_cbranch_scc0 .LBB0_162
	s_and_b64 vcc, exec, s[6:7]
	s_cbranch_vccz .LBB0_165
	s_barrier

; #define PG8_STAGE(bufoff, gbase, voff) do { _Pragma("unroll") for (int _i = 0; _i < 2; ++_i) \
;         __builtin_amdgcn_global_load_lds((const unsigned*)((const char*)(gbase) + (voff)[_i]), (PG8_LAS unsigned*)(lds + (bufoff) + ldsw + _i * 8192), 16, 0, 0); } while (0)
; #define PG8_WAIT_V(n) asm volatile("s_waitcnt vmcnt(" #n ")" ::: "memory")
; #define PG8_BAR __builtin_amdgcn_s_barrier()
; template <class Epi, class Sched, bool ALIGN_EPI = false, bool SP2 = false>
; __device__ __forceinline__ void gemm_phase(PG8_LAS unsigned char* lds, const Gemm g, const Sched& S, const Epi& E, volatile PG8_LAS unsigned* sw = nullptr) {
;     ...
;     const int tid = tid_, wid = __builtin_amdgcn_readfirstlane(tid >> 6), lane = tid & 63, wr = wid >> 2, wc = wid & 3, fr = lane & 15, fq = lane >> 4;
;     const int K = g.K, nt = K / BK;
;     unsigned voffA[2], voffB[2];
; #pragma unroll
;     for (int i = 0; i < 2; ++i) { int R, C; stage_rc(tid * 16 + i * 8192, R, C); const int Rb = Epi::PERM ? ((R & ~31) + perm32(R & 31)) : R;
;         const int Ra = Epi::PERMA ? ((R & 64) + 4 * (R & 15) + ((R >> 4) & 3)) : R;
;         voffA[i] = (unsigned)(Ra * BK + C) * 2u; voffB[i] = (unsigned)(Rb * BK + C) * 2u; }
;     const size_t kstep = (size_t)(BM * BK * 2);
;     const size_t hstep = (size_t)HALF * BK * 2;
;     const size_t tstep = (size_t)K * BM * 2;
;     const unsigned ldsw = (unsigned)wid * 1024u;
;     const int aoff = lds_byte(wr * 64 + fr, fq * 8), boff = lds_byte(wc * 32 + fr, fq * 8);
;     ...
;         PG8_WAIT_V(2); PG8_BAR;
;         PG8_STAGE(PG8_SB(1, 0), cB + kstep, voffB); PG8_STAGE(PG8_SA(1, 0), cA + kstep, voffA); PG8_STAGE(PG8_SB(1, 1), cB + hstep + kstep, voffB);
;         PG8_WAIT_V(6); PG8_BAR;
.LBB0_438:
	s_add_u32 s8, s48, 0x8000
	s_addc_u32 s9, s49, 0
	s_add_u32 s22, s46, 0x8000
	s_addc_u32 s23, s47, 0
	s_add_u32 s24, s48, 0xc000
	s_addc_u32 s25, s49, 0
	s_add_i32 m0, s13, 0x18000
	v_lshl_add_u64 v[10:11], s[8:9], 0, v[150:151]
	s_waitcnt vmcnt(2)
	s_barrier
	global_load_lds_dwordx4 v[10:11], off
	v_lshl_add_u64 v[10:11], s[8:9], 0, v[146:147]
	s_add_i32 m0, s13, 0x1a000
	s_add_i32 s41, s13, 0x8000
	global_load_lds_dwordx4 v[10:11], off
	v_lshl_add_u64 v[10:11], s[22:23], 0, v[152:153]
	s_mov_b32 m0, s41
	s_add_i32 s42, s13, 0xa000
	global_load_lds_dwordx4 v[10:11], off
	v_lshl_add_u64 v[10:11], s[22:23], 0, v[148:149]
	s_mov_b32 m0, s42
	v_bfe_u32 v172, v2, 4, 2
	global_load_lds_dwordx4 v[10:11], off
	s_add_i32 m0, s13, 0x1c000
	v_lshl_add_u64 v[10:11], s[24:25], 0, v[150:151]
	global_load_lds_dwordx4 v[10:11], off
	v_lshl_add_u64 v[10:11], s[24:25], 0, v[146:147]
	s_add_i32 m0, s13, 0x1e000
	v_and_b32_e32 v1, 15, v2
	global_load_lds_dwordx4 v[10:11], off
	v_lshlrev_b32_e32 v9, 4, v172
	v_lshlrev_b32_e32 v2, 2, v2
	s_and_b32 s7, s6, 3
	s_lshl_b32 s43, s5, 6
	v_lshl_or_b32 v9, v1, 6, v9
	s_lshl_b32 s5, s5, 13
	v_and_b32_e32 v2, 32, v2
	v_bitop3_b32 v10, v9, s5, v2 bitop3:0xde
	s_lshl_b32 s5, s7, 12
	v_bitop3_b32 v173, v9, s5, v2 bitop3:0xde
	v_lshlrev_b32_e32 v2, 10, v7
	v_and_b32_e32 v2, 0xfffff800, v2
	v_lshl_add_u32 v2, v6, 7, v2
	v_and_b32_e32 v6, 1, v7
	v_lshl_or_b32 v2, v6, 6, v2
	v_lshl_add_u32 v156, v8, 1, v2
	v_lshlrev_b32_e32 v2, 10, v3
	s_lshl_b32 s54, s7, 5
	v_and_b32_e32 v2, 0xfffff800, v2
	s_waitcnt vmcnt(6)
	s_cmpk_lt_u32 s4, 0x100
	v_lshl_add_u32 v2, v4, 7, v2
	v_and_b32_e32 v3, 1, v3
	s_cselect_b64 s[4:5], -1, 0
	v_lshl_or_b32 v2, v3, 6, v2
	s_add_i32 s57, 0, 0x10000
	s_add_i32 s58, 0, 0x14000
	s_bfe_u32 s55, s6, 0x10001
	s_and_b32 s56, s54, 32
	v_mov_b32_e32 v157, v155
	v_lshl_add_u32 v158, v5, 1, v2
	v_mov_b32_e32 v159, v155
	v_add_u32_e32 v174, s57, v173
	v_add_u32_e32 v175, s58, v173
	v_add_u32_e32 v176, 0, v10
	s_mov_b64 s[6:7], 0xb0200
	s_mov_b32 s59, 0x15000
	s_mov_b32 s30, s10
	s_mov_b32 s65, s12
	s_mov_b32 s64, 0
	s_barrier
	s_mov_b32 s99, 0
	s_branch .LBB0_441

; template <class Epi, class Sched, bool ALIGN_EPI = false, bool SP2 = false>
; __device__ __forceinline__ void gemm_phase(PG8_LAS unsigned char* lds, const Gemm g, const Sched& S, const Epi& E, volatile PG8_LAS unsigned* sw = nullptr) {
;     ...
;         if (!has_next) break;
; #pragma unroll
;         for (int a = 0; a < 2; ++a)
; #pragma unroll
;             for (int b = 0; b < 2; ++b)
; #pragma unroll
;                 for (int m = 0; m < 4; ++m)
; #pragma unroll
;                     for (int n = 0; n < 2; ++n) acc[a][b][m][n] = (f32x4){0.f, 0.f, 0.f, 0.f};
;         cur = nxt; cA = nA; cB = nB; ++ui;
.LBB0_440:
	s_andn2_b64 vcc, exec, s[26:27]
	s_mov_b32 s30, s22
	s_mov_b32 s65, s8
	s_mov_b64 s[48:49], s[28:29]
	s_mov_b64 s[46:47], s[24:25]
	s_cbranch_vccz .LBB0_456
	s_mov_b32 s99, 1

; #define PG8_STAGE(bufoff, gbase, voff) do { _Pragma("unroll") for (int _i = 0; _i < 2; ++_i) \
;         __builtin_amdgcn_global_load_lds((const unsigned*)((const char*)(gbase) + (voff)[_i]), (PG8_LAS unsigned*)(lds + (bufoff) + ldsw + _i * 8192), 16, 0, 0); } while (0)
; #define PG8_LDA(dst, b, h) do { _Pragma("unroll") for (int m = 0; m < 4; ++m) _Pragma("unroll") for (int k = 0; k < 2; ++k) dst[m][k] = *(const PG8_LAS bf16x8*)(lds + PG8_SA(b, h) + aoff + m * 2048 + k * 1024); } while (0)
; #define PG8_LDB(dst, b, h) do { _Pragma("unroll") for (int n = 0; n < 2; ++n) _Pragma("unroll") for (int k = 0; k < 2; ++k) dst[n][k] = *(const PG8_LAS bf16x8*)(lds + PG8_SB(b, h) + boff + n * 2048 + k * 1024); } while (0)
; #define PG8_MMA(ai, bj, At, Bt) do { __builtin_amdgcn_s_setprio(1); _Pragma("unroll") for (int m = 0; m < 4; ++m) _Pragma("unroll") for (int n = 0; n < 2; ++n) _Pragma("unroll") for (int k = 0; k < 2; ++k) \
;         acc[ai][bj][m][n] = __builtin_amdgcn_mfma_f32_16x16x32_bf16(Bt[n][k], At[m][k], acc[ai][bj][m][n], 0, 0, 0); __builtin_amdgcn_s_setprio(0); } while (0)
; #define PG8_WAIT_V(n) asm volatile("s_waitcnt vmcnt(" #n ")" ::: "memory")
; #define PG8_WAIT_L(n) asm volatile("s_waitcnt lgkmcnt(" #n ")" ::: "memory")
; #define PG8_BAR __builtin_amdgcn_s_barrier()
; #define PG8_SCHED __builtin_amdgcn_sched_barrier(0)
; template <class Epi, class Sched, bool ALIGN_EPI = false, bool SP2 = false>
; __device__ __forceinline__ void gemm_phase(PG8_LAS unsigned char* lds, const Gemm g, const Sched& S, const Epi& E, volatile PG8_LAS unsigned* sw = nullptr) {
;     ...
;             PG8_LDB(B0, 0, 0); PG8_LDB(B1, 0, 1); PG8_SCHED; PG8_LDA(At, 0, 0); PG8_STAGE(PG8_SA(1, 1), a1 + hstep, voffA);
;             PG8_WAIT_V(8); PG8_WAIT_L(0); PG8_BAR; PG8_MMA(0, 0, At, B0); PG8_MMA(0, 1, At, B1); PG8_BAR; PG8_SCHED;
;             PG8_LDA(At, 0, 1); PG8_STAGE(PG8_SB(0, 0), b2, voffB); PG8_STAGE(PG8_SB(0, 1), b2 + hstep, voffB); PG8_STAGE(PG8_SA(0, 0), a2, voffA);
;             PG8_WAIT_V(8); PG8_WAIT_L(0); PG8_BAR; PG8_MMA(1, 0, At, B0); PG8_MMA(1, 1, At, B1); PG8_BAR; PG8_SCHED;
.LBB0_444:
	ds_read_b128 v[130:133], v174
	ds_read_b128 v[134:137], v174 offset:1024
	ds_read_b128 v[138:141], v174 offset:2048
	ds_read_b128 v[142:145], v174 offset:3072
	ds_read_b128 v[160:163], v175
	ds_read_b128 v[164:167], v175 offset:1024
	ds_read_b128 v[168:171], v175 offset:2048
	ds_read_b128 v[178:181], v175 offset:3072
	s_add_u32 s48, s46, 0x4000
	s_addc_u32 s49, s47, 0
	s_cmp_eq_u32 s80, 12
	s_cselect_b32 s52, s31, s48
	s_cselect_b32 s53, s9, s49
	s_cselect_b32 s50, s73, s74
	s_cselect_b32 s51, s23, s75
	s_add_u32 s48, s52, 0x8000
	s_addc_u32 s49, s53, 0
	v_lshl_add_u64 v[214:215], s[46:47], 0, v[156:157]
	s_add_i32 m0, s13, 0xc000
	ds_read_b128 v[182:185], v176
	ds_read_b128 v[186:189], v176 offset:1024
	ds_read_b128 v[190:193], v176 offset:2048
	ds_read_b128 v[194:197], v176 offset:3072
	ds_read_b128 v[198:201], v176 offset:4096
	ds_read_b128 v[202:205], v176 offset:5120
	ds_read_b128 v[206:209], v176 offset:6144
	ds_read_b128 v[210:213], v176 offset:7168
	global_load_lds_dwordx4 v[214:215], off
	v_lshl_add_u64 v[214:215], s[46:47], 0, v[158:159]
	s_add_i32 m0, s13, 0xe000
	s_nop 0
	global_load_lds_dwordx4 v[214:215], off
	s_cmp_lg_u32 s99, 0
	s_cbranch_scc1 .Lrx_p4_0_r
	s_waitcnt vmcnt(8)
	s_branch .Lrx_p4_0_j
.Lrx_p4_0_r:
	s_waitcnt vmcnt(63)
.Lrx_p4_0_j:
	s_waitcnt lgkmcnt(0)
	s_barrier
	s_setprio 1
	s_waitcnt lgkmcnt(0)
	v_mfma_f32_16x16x32_bf16 v[126:129], v[130:133], v[182:185], v[126:129]
	v_mfma_f32_16x16x32_bf16 v[122:125], v[138:141], v[182:185], v[122:125]
	v_mfma_f32_16x16x32_bf16 v[118:121], v[130:133], v[190:193], v[118:121]
	v_mfma_f32_16x16x32_bf16 v[114:117], v[138:141], v[190:193], v[114:117]
	v_mfma_f32_16x16x32_bf16 v[110:113], v[130:133], v[198:201], v[110:113]
	v_mfma_f32_16x16x32_bf16 v[106:109], v[138:141], v[198:201], v[106:109]
	v_mfma_f32_16x16x32_bf16 v[102:105], v[130:133], v[206:209], v[102:105]
	v_mfma_f32_16x16x32_bf16 v[98:101], v[138:141], v[206:209], v[98:101]
	v_mfma_f32_16x16x32_bf16 v[126:129], v[134:137], v[186:189], v[126:129]
	v_mfma_f32_16x16x32_bf16 v[122:125], v[142:145], v[186:189], v[122:125]
	v_mfma_f32_16x16x32_bf16 v[118:121], v[134:137], v[194:197], v[118:121]
	v_mfma_f32_16x16x32_bf16 v[114:117], v[142:145], v[194:197], v[114:117]
	v_mfma_f32_16x16x32_bf16 v[110:113], v[134:137], v[202:205], v[110:113]
	v_mfma_f32_16x16x32_bf16 v[106:109], v[142:145], v[202:205], v[106:109]
	v_mfma_f32_16x16x32_bf16 v[102:105], v[134:137], v[210:213], v[102:105]
	v_mfma_f32_16x16x32_bf16 v[98:101], v[142:145], v[210:213], v[98:101]
	s_setprio 0
	s_setprio 1
	v_mfma_f32_16x16x32_bf16 v[66:69], v[160:163], v[182:185], v[66:69]
	v_mfma_f32_16x16x32_bf16 v[58:61], v[168:171], v[182:185], v[58:61]
	v_mfma_f32_16x16x32_bf16 v[54:57], v[160:163], v[190:193], v[54:57]
	v_mfma_f32_16x16x32_bf16 v[50:53], v[168:171], v[190:193], v[50:53]
	v_mfma_f32_16x16x32_bf16 v[46:49], v[160:163], v[198:201], v[46:49]
	v_mfma_f32_16x16x32_bf16 v[42:45], v[168:171], v[198:201], v[42:45]
	v_mfma_f32_16x16x32_bf16 v[38:41], v[160:163], v[206:209], v[38:41]
	v_mfma_f32_16x16x32_bf16 v[34:37], v[168:171], v[206:209], v[34:37]
	v_mfma_f32_16x16x32_bf16 v[66:69], v[164:167], v[186:189], v[66:69]
	v_mfma_f32_16x16x32_bf16 v[58:61], v[178:181], v[186:189], v[58:61]
	v_mfma_f32_16x16x32_bf16 v[54:57], v[164:167], v[194:197], v[54:57]
	v_mfma_f32_16x16x32_bf16 v[50:53], v[178:181], v[194:197], v[50:53]
	v_mfma_f32_16x16x32_bf16 v[46:49], v[164:167], v[202:205], v[46:49]
	v_mfma_f32_16x16x32_bf16 v[42:45], v[178:181], v[202:205], v[42:45]
	v_mfma_f32_16x16x32_bf16 v[38:41], v[164:167], v[210:213], v[38:41]
	v_mfma_f32_16x16x32_bf16 v[34:37], v[178:181], v[210:213], v[34:37]
	s_setprio 0
	s_barrier
	s_add_i32 s81, s57, s11
	v_lshl_add_u64 v[214:215], s[50:51], 0, v[150:151]
	s_mov_b32 m0, s81
	ds_read_b128 v[182:185], v176 offset:16384
	ds_read_b128 v[186:189], v176 offset:17408
	ds_read_b128 v[190:193], v176 offset:18432
	ds_read_b128 v[194:197], v176 offset:19456
	ds_read_b128 v[198:201], v176 offset:20480
	ds_read_b128 v[202:205], v176 offset:21504
	ds_read_b128 v[206:209], v176 offset:22528
	ds_read_b128 v[210:213], v176 offset:23552
	global_load_lds_dwordx4 v[214:215], off
	s_add_i32 m0, s81, 0x2000
	s_add_u32 s82, s50, 0x4000
	v_lshl_add_u64 v[214:215], s[50:51], 0, v[146:147]
	s_addc_u32 s83, s51, 0
	s_add_i32 s81, s58, s11
	global_load_lds_dwordx4 v[214:215], off
	v_lshl_add_u64 v[214:215], s[82:83], 0, v[150:151]
	s_mov_b32 m0, s81
	s_nop 0
	global_load_lds_dwordx4 v[214:215], off
	v_lshl_add_u64 v[214:215], s[82:83], 0, v[146:147]
	s_add_i32 m0, s81, 0x2000
	s_nop 0
	global_load_lds_dwordx4 v[214:215], off
	v_lshl_add_u64 v[214:215], s[52:53], 0, v[152:153]
	s_mov_b32 m0, s13
	s_nop 0
	global_load_lds_dwordx4 v[214:215], off
	v_lshl_add_u64 v[214:215], s[52:53], 0, v[148:149]
	s_mov_b32 m0, s14
	s_nop 0
	global_load_lds_dwordx4 v[214:215], off
	s_cmp_lg_u32 s99, 0
	s_cbranch_scc1 .Lrx_p4_1_r
	s_waitcnt vmcnt(8)
	s_branch .Lrx_p4_1_j

; #define PG8_STAGE(bufoff, gbase, voff) do { _Pragma("unroll") for (int _i = 0; _i < 2; ++_i) \
;         __builtin_amdgcn_global_load_lds((const unsigned*)((const char*)(gbase) + (voff)[_i]), (PG8_LAS unsigned*)(lds + (bufoff) + ldsw + _i * 8192), 16, 0, 0); } while (0)
; #define PG8_LDA(dst, b, h) do { _Pragma("unroll") for (int m = 0; m < 4; ++m) _Pragma("unroll") for (int k = 0; k < 2; ++k) dst[m][k] = *(const PG8_LAS bf16x8*)(lds + PG8_SA(b, h) + aoff + m * 2048 + k * 1024); } while (0)
; #define PG8_LDB(dst, b, h) do { _Pragma("unroll") for (int n = 0; n < 2; ++n) _Pragma("unroll") for (int k = 0; k < 2; ++k) dst[n][k] = *(const PG8_LAS bf16x8*)(lds + PG8_SB(b, h) + boff + n * 2048 + k * 1024); } while (0)
; #define PG8_MMA(ai, bj, At, Bt) do { __builtin_amdgcn_s_setprio(1); _Pragma("unroll") for (int m = 0; m < 4; ++m) _Pragma("unroll") for (int n = 0; n < 2; ++n) _Pragma("unroll") for (int k = 0; k < 2; ++k) \
;         acc[ai][bj][m][n] = __builtin_amdgcn_mfma_f32_16x16x32_bf16(Bt[n][k], At[m][k], acc[ai][bj][m][n], 0, 0, 0); __builtin_amdgcn_s_setprio(0); } while (0)
; #define PG8_WAIT_V(n) asm volatile("s_waitcnt vmcnt(" #n ")" ::: "memory")
; #define PG8_WAIT_L(n) asm volatile("s_waitcnt lgkmcnt(" #n ")" ::: "memory")
; #define PG8_BAR __builtin_amdgcn_s_barrier()
; #define PG8_SCHED __builtin_amdgcn_sched_barrier(0)
; template <class Epi, class Sched, bool ALIGN_EPI = false, bool SP2 = false>
; __device__ __forceinline__ void gemm_phase(PG8_LAS unsigned char* lds, const Gemm g, const Sched& S, const Epi& E, volatile PG8_LAS unsigned* sw = nullptr) {
;     ...
;             PG8_WAIT_V(8); PG8_WAIT_L(0); PG8_BAR; PG8_MMA(1, 0, At, B0); PG8_MMA(1, 1, At, B1); PG8_BAR; PG8_SCHED;
;             PG8_LDB(B0, 1, 0); PG8_LDB(B1, 1, 1); PG8_SCHED; PG8_LDA(At, 1, 0); PG8_STAGE(PG8_SA(0, 1), a2 + hstep, voffA);
;             PG8_WAIT_V(8); PG8_WAIT_L(0); PG8_BAR; PG8_MMA(0, 0, At, B0); PG8_MMA(0, 1, At, B1); PG8_BAR; PG8_SCHED;
.Lrx_p4_1_j:
	s_mov_b32 s99, 0
	s_waitcnt lgkmcnt(0)
	s_barrier
	s_setprio 1
	s_waitcnt lgkmcnt(0)
	v_mfma_f32_16x16x32_bf16 v[94:97], v[130:133], v[182:185], v[94:97]
	v_mfma_f32_16x16x32_bf16 v[90:93], v[138:141], v[182:185], v[90:93]
	v_mfma_f32_16x16x32_bf16 v[86:89], v[130:133], v[190:193], v[86:89]
	v_mfma_f32_16x16x32_bf16 v[82:85], v[138:141], v[190:193], v[82:85]
	v_mfma_f32_16x16x32_bf16 v[78:81], v[130:133], v[198:201], v[78:81]
	v_mfma_f32_16x16x32_bf16 v[74:77], v[138:141], v[198:201], v[74:77]
	v_mfma_f32_16x16x32_bf16 v[70:73], v[130:133], v[206:209], v[70:73]
	v_mfma_f32_16x16x32_bf16 v[62:65], v[138:141], v[206:209], v[62:65]
	v_mfma_f32_16x16x32_bf16 v[94:97], v[134:137], v[186:189], v[94:97]
	v_mfma_f32_16x16x32_bf16 v[90:93], v[142:145], v[186:189], v[90:93]
	v_mfma_f32_16x16x32_bf16 v[86:89], v[134:137], v[194:197], v[86:89]
	v_mfma_f32_16x16x32_bf16 v[82:85], v[142:145], v[194:197], v[82:85]
	v_mfma_f32_16x16x32_bf16 v[78:81], v[134:137], v[202:205], v[78:81]
	v_mfma_f32_16x16x32_bf16 v[74:77], v[142:145], v[202:205], v[74:77]
	v_mfma_f32_16x16x32_bf16 v[70:73], v[134:137], v[210:213], v[70:73]
	v_mfma_f32_16x16x32_bf16 v[62:65], v[142:145], v[210:213], v[62:65]
	s_setprio 0
	s_setprio 1
	v_mfma_f32_16x16x32_bf16 v[30:33], v[160:163], v[182:185], v[30:33]
	v_mfma_f32_16x16x32_bf16 v[26:29], v[168:171], v[182:185], v[26:29]
	v_mfma_f32_16x16x32_bf16 v[22:25], v[160:163], v[190:193], v[22:25]
	v_mfma_f32_16x16x32_bf16 v[18:21], v[168:171], v[190:193], v[18:21]
	v_mfma_f32_16x16x32_bf16 v[14:17], v[160:163], v[198:201], v[14:17]
	v_mfma_f32_16x16x32_bf16 v[10:13], v[168:171], v[198:201], v[10:13]
	v_mfma_f32_16x16x32_bf16 v[6:9], v[160:163], v[206:209], v[6:9]
	v_mfma_f32_16x16x32_bf16 v[2:5], v[168:171], v[206:209], v[2:5]
	v_mfma_f32_16x16x32_bf16 v[30:33], v[164:167], v[186:189], v[30:33]
	v_mfma_f32_16x16x32_bf16 v[26:29], v[178:181], v[186:189], v[26:29]
	v_mfma_f32_16x16x32_bf16 v[22:25], v[164:167], v[194:197], v[22:25]
	v_mfma_f32_16x16x32_bf16 v[18:21], v[178:181], v[194:197], v[18:21]
	v_mfma_f32_16x16x32_bf16 v[14:17], v[164:167], v[202:205], v[14:17]
	v_mfma_f32_16x16x32_bf16 v[10:13], v[178:181], v[202:205], v[10:13]
	v_mfma_f32_16x16x32_bf16 v[6:9], v[164:167], v[210:213], v[6:9]
	v_mfma_f32_16x16x32_bf16 v[2:5], v[178:181], v[210:213], v[2:5]
	s_setprio 0
	s_barrier
	s_add_i32 s81, 0, 0x18000
	s_add_i32 s82, 0, 0x1c000
	v_add_u32_e32 v142, s81, v173
	v_add_u32_e32 v154, s82, v173
	ds_read_b128 v[130:133], v142
	ds_read_b128 v[134:137], v142 offset:1024
	ds_read_b128 v[138:141], v142 offset:2048
	ds_read_b128 v[142:145], v142 offset:3072
	ds_read_b128 v[160:163], v154
	ds_read_b128 v[164:167], v154 offset:1024
	ds_read_b128 v[168:171], v154 offset:2048
	ds_read_b128 v[178:181], v154 offset:3072
	s_add_u32 s52, s52, 0x4000
	s_addc_u32 s53, s53, 0
	s_mov_b32 m0, s15
	v_lshl_add_u64 v[214:215], s[52:53], 0, v[152:153]
	ds_read_b128 v[182:185], v176 offset:32768
	ds_read_b128 v[186:189], v176 offset:33792
	ds_read_b128 v[190:193], v176 offset:34816
	ds_read_b128 v[194:197], v176 offset:35840
	ds_read_b128 v[198:201], v176 offset:36864
	ds_read_b128 v[202:205], v176 offset:37888
	ds_read_b128 v[206:209], v176 offset:38912
	ds_read_b128 v[210:213], v176 offset:39936
	global_load_lds_dwordx4 v[214:215], off
	v_lshl_add_u64 v[214:215], s[52:53], 0, v[148:149]
	s_mov_b32 m0, s33
	s_nop 0
	global_load_lds_dwordx4 v[214:215], off
	s_waitcnt vmcnt(8)
	s_waitcnt lgkmcnt(0)
	s_barrier
	s_setprio 1
	s_waitcnt lgkmcnt(0)
	v_mfma_f32_16x16x32_bf16 v[126:129], v[130:133], v[182:185], v[126:129]
	v_mfma_f32_16x16x32_bf16 v[122:125], v[138:141], v[182:185], v[122:125]
	v_mfma_f32_16x16x32_bf16 v[118:121], v[130:133], v[190:193], v[118:121]
	v_mfma_f32_16x16x32_bf16 v[114:117], v[138:141], v[190:193], v[114:117]
	v_mfma_f32_16x16x32_bf16 v[110:113], v[130:133], v[198:201], v[110:113]
	v_mfma_f32_16x16x32_bf16 v[106:109], v[138:141], v[198:201], v[106:109]
	v_mfma_f32_16x16x32_bf16 v[102:105], v[130:133], v[206:209], v[102:105]
	v_mfma_f32_16x16x32_bf16 v[98:101], v[138:141], v[206:209], v[98:101]
	v_mfma_f32_16x16x32_bf16 v[126:129], v[134:137], v[186:189], v[126:129]
	v_mfma_f32_16x16x32_bf16 v[122:125], v[142:145], v[186:189], v[122:125]
	v_mfma_f32_16x16x32_bf16 v[118:121], v[134:137], v[194:197], v[118:121]
	v_mfma_f32_16x16x32_bf16 v[114:117], v[142:145], v[194:197], v[114:117]
	v_mfma_f32_16x16x32_bf16 v[110:113], v[134:137], v[202:205], v[110:113]
	v_mfma_f32_16x16x32_bf16 v[106:109], v[142:145], v[202:205], v[106:109]
	v_mfma_f32_16x16x32_bf16 v[102:105], v[134:137], v[210:213], v[102:105]
	v_mfma_f32_16x16x32_bf16 v[98:101], v[142:145], v[210:213], v[98:101]
	s_setprio 0
	s_setprio 1
	v_mfma_f32_16x16x32_bf16 v[66:69], v[160:163], v[182:185], v[66:69]
	v_mfma_f32_16x16x32_bf16 v[58:61], v[168:171], v[182:185], v[58:61]
	v_mfma_f32_16x16x32_bf16 v[54:57], v[160:163], v[190:193], v[54:57]
	v_mfma_f32_16x16x32_bf16 v[50:53], v[168:171], v[190:193], v[50:53]
	v_mfma_f32_16x16x32_bf16 v[46:49], v[160:163], v[198:201], v[46:49]
	v_mfma_f32_16x16x32_bf16 v[42:45], v[168:171], v[198:201], v[42:45]
	v_mfma_f32_16x16x32_bf16 v[38:41], v[160:163], v[206:209], v[38:41]
	v_mfma_f32_16x16x32_bf16 v[34:37], v[168:171], v[206:209], v[34:37]
	v_mfma_f32_16x16x32_bf16 v[66:69], v[164:167], v[186:189], v[66:69]
	v_mfma_f32_16x16x32_bf16 v[58:61], v[178:181], v[186:189], v[58:61]
	v_mfma_f32_16x16x32_bf16 v[54:57], v[164:167], v[194:197], v[54:57]
	v_mfma_f32_16x16x32_bf16 v[50:53], v[178:181], v[194:197], v[50:53]
	v_mfma_f32_16x16x32_bf16 v[46:49], v[164:167], v[202:205], v[46:49]
	v_mfma_f32_16x16x32_bf16 v[42:45], v[178:181], v[202:205], v[42:45]
	v_mfma_f32_16x16x32_bf16 v[38:41], v[164:167], v[210:213], v[38:41]
	v_mfma_f32_16x16x32_bf16 v[34:37], v[178:181], v[210:213], v[34:37]
	s_setprio 0
	s_barrier
; #define PG8_STAGE(bufoff, gbase, voff) do { _Pragma("unroll") for (int _i = 0; _i < 2; ++_i) \
;         __builtin_amdgcn_global_load_lds((const unsigned*)((const char*)(gbase) + (voff)[_i]), (PG8_LAS unsigned*)(lds + (bufoff) + ldsw + _i * 8192), 16, 0, 0); } while (0)
; #define PG8_LDA(dst, b, h) do { _Pragma("unroll") for (int m = 0; m < 4; ++m) _Pragma("unroll") for (int k = 0; k < 2; ++k) dst[m][k] = *(const PG8_LAS bf16x8*)(lds + PG8_SA(b, h) + aoff + m * 2048 + k * 1024); } while (0)
; #define PG8_MMA(ai, bj, At, Bt) do { __builtin_amdgcn_s_setprio(1); _Pragma("unroll") for (int m = 0; m < 4; ++m) _Pragma("unroll") for (int n = 0; n < 2; ++n) _Pragma("unroll") for (int k = 0; k < 2; ++k) \
;         acc[ai][bj][m][n] = __builtin_amdgcn_mfma_f32_16x16x32_bf16(Bt[n][k], At[m][k], acc[ai][bj][m][n], 0, 0, 0); __builtin_amdgcn_s_setprio(0); } while (0)
; #define PG8_WAIT_V(n) asm volatile("s_waitcnt vmcnt(" #n ")" ::: "memory")
; #define PG8_WAIT_L(n) asm volatile("s_waitcnt lgkmcnt(" #n ")" ::: "memory")
; #define PG8_BAR __builtin_amdgcn_s_barrier()
; #define PG8_SCHED __builtin_amdgcn_sched_barrier(0)
; template <class Epi, class Sched, bool ALIGN_EPI = false, bool SP2 = false>
; __device__ __forceinline__ void gemm_phase(PG8_LAS unsigned char* lds, const Gemm g, const Sched& S, const Epi& E, volatile PG8_LAS unsigned* sw = nullptr) {
;     ...
;             PG8_LDA(At, 1, 1); PG8_STAGE(PG8_SB(1, 0), b3, voffB); PG8_STAGE(PG8_SB(1, 1), b3 + hstep, voffB); PG8_STAGE(PG8_SA(1, 0), a3, voffA);
;             PG8_WAIT_V(8); PG8_WAIT_L(0); PG8_BAR; PG8_MMA(1, 0, At, B0); PG8_MMA(1, 1, At, B1); PG8_BAR; PG8_SCHED;
;     ...
;         if constexpr (ALIGN_EPI) { if (wr == 0) PG8_BAR; }
	s_add_u32 s52, s50, 0x8000
	s_addc_u32 s53, s51, 0
	s_add_i32 s81, s81, s11
	v_lshl_add_u64 v[214:215], s[52:53], 0, v[150:151]
	s_mov_b32 m0, s81
	ds_read_b128 v[182:185], v176 offset:49152
	ds_read_b128 v[186:189], v176 offset:50176
	ds_read_b128 v[190:193], v176 offset:51200
	ds_read_b128 v[194:197], v176 offset:52224
	ds_read_b128 v[198:201], v176 offset:53248
	ds_read_b128 v[202:205], v176 offset:54272
	ds_read_b128 v[206:209], v176 offset:55296
	ds_read_b128 v[210:213], v176 offset:56320
	global_load_lds_dwordx4 v[214:215], off
	s_add_i32 m0, s81, 0x2000
	s_add_u32 s50, s50, 0xc000
	v_lshl_add_u64 v[214:215], s[52:53], 0, v[146:147]
	s_addc_u32 s51, s51, 0
	s_add_i32 s52, s82, s11
	global_load_lds_dwordx4 v[214:215], off
	v_lshl_add_u64 v[214:215], s[50:51], 0, v[150:151]
	s_mov_b32 m0, s52
	s_nop 0
	global_load_lds_dwordx4 v[214:215], off
	v_lshl_add_u64 v[214:215], s[50:51], 0, v[146:147]
	s_add_i32 m0, s52, 0x2000
	s_nop 0
	global_load_lds_dwordx4 v[214:215], off
	v_lshl_add_u64 v[214:215], s[48:49], 0, v[152:153]
	s_mov_b32 m0, s41
	s_nop 0
	global_load_lds_dwordx4 v[214:215], off
	v_lshl_add_u64 v[214:215], s[48:49], 0, v[148:149]
	s_mov_b32 m0, s42
	s_nop 0
	global_load_lds_dwordx4 v[214:215], off
	s_waitcnt vmcnt(8)
	s_waitcnt lgkmcnt(0)
	s_barrier
	s_setprio 1
	s_waitcnt lgkmcnt(0)
	v_mfma_f32_16x16x32_bf16 v[94:97], v[130:133], v[182:185], v[94:97]
	v_mfma_f32_16x16x32_bf16 v[90:93], v[138:141], v[182:185], v[90:93]
	v_mfma_f32_16x16x32_bf16 v[86:89], v[130:133], v[190:193], v[86:89]
	v_mfma_f32_16x16x32_bf16 v[82:85], v[138:141], v[190:193], v[82:85]
	v_mfma_f32_16x16x32_bf16 v[78:81], v[130:133], v[198:201], v[78:81]
	v_mfma_f32_16x16x32_bf16 v[74:77], v[138:141], v[198:201], v[74:77]
	v_mfma_f32_16x16x32_bf16 v[70:73], v[130:133], v[206:209], v[70:73]
	v_mfma_f32_16x16x32_bf16 v[62:65], v[138:141], v[206:209], v[62:65]
	v_mfma_f32_16x16x32_bf16 v[94:97], v[134:137], v[186:189], v[94:97]
	v_mfma_f32_16x16x32_bf16 v[90:93], v[142:145], v[186:189], v[90:93]
	v_mfma_f32_16x16x32_bf16 v[86:89], v[134:137], v[194:197], v[86:89]
	v_mfma_f32_16x16x32_bf16 v[82:85], v[142:145], v[194:197], v[82:85]
	v_mfma_f32_16x16x32_bf16 v[78:81], v[134:137], v[202:205], v[78:81]
	v_mfma_f32_16x16x32_bf16 v[74:77], v[142:145], v[202:205], v[74:77]
	v_mfma_f32_16x16x32_bf16 v[70:73], v[134:137], v[210:213], v[70:73]
	v_mfma_f32_16x16x32_bf16 v[62:65], v[142:145], v[210:213], v[62:65]
	s_setprio 0
	s_setprio 1
	v_mfma_f32_16x16x32_bf16 v[30:33], v[160:163], v[182:185], v[30:33]
	v_mfma_f32_16x16x32_bf16 v[26:29], v[168:171], v[182:185], v[26:29]
	v_mfma_f32_16x16x32_bf16 v[22:25], v[160:163], v[190:193], v[22:25]
	v_mfma_f32_16x16x32_bf16 v[18:21], v[168:171], v[190:193], v[18:21]
	v_mfma_f32_16x16x32_bf16 v[14:17], v[160:163], v[198:201], v[14:17]
	v_mfma_f32_16x16x32_bf16 v[10:13], v[168:171], v[198:201], v[10:13]
	v_mfma_f32_16x16x32_bf16 v[6:9], v[160:163], v[206:209], v[6:9]
	v_mfma_f32_16x16x32_bf16 v[2:5], v[168:171], v[206:209], v[2:5]
	v_mfma_f32_16x16x32_bf16 v[30:33], v[164:167], v[186:189], v[30:33]
	v_mfma_f32_16x16x32_bf16 v[26:29], v[178:181], v[186:189], v[26:29]
	v_mfma_f32_16x16x32_bf16 v[22:25], v[164:167], v[194:197], v[22:25]
	v_mfma_f32_16x16x32_bf16 v[18:21], v[178:181], v[194:197], v[18:21]
	v_mfma_f32_16x16x32_bf16 v[14:17], v[164:167], v[202:205], v[14:17]
	v_mfma_f32_16x16x32_bf16 v[10:13], v[178:181], v[202:205], v[10:13]
	v_mfma_f32_16x16x32_bf16 v[6:9], v[164:167], v[210:213], v[6:9]
	v_mfma_f32_16x16x32_bf16 v[2:5], v[178:181], v[210:213], v[2:5]
	s_setprio 0
	s_barrier
	s_add_i32 s80, s80, 2
	s_add_u32 s46, s46, 0x10000
	s_addc_u32 s47, s47, 0
	s_add_u32 s74, s74, 0x10000
	s_addc_u32 s75, s75, 0
	s_cmp_gt_u32 s80, 13
	s_cbranch_scc0 .LBB0_444
	s_and_b64 vcc, exec, s[4:5]
	s_cbranch_vccz .LBB0_447
	s_barrier

; #define PG8_STAGE(bufoff, gbase, voff) do { _Pragma("unroll") for (int _i = 0; _i < 2; ++_i) \
;         __builtin_amdgcn_global_load_lds((const unsigned*)((const char*)(gbase) + (voff)[_i]), (PG8_LAS unsigned*)(lds + (bufoff) + ldsw + _i * 8192), 16, 0, 0); } while (0)
; #define PG8_WAIT_V(n) asm volatile("s_waitcnt vmcnt(" #n ")" ::: "memory")
; #define PG8_BAR __builtin_amdgcn_s_barrier()
; #define LAS __attribute__((address_space(3)))
; template <class Epi, class Sched, bool ALIGN_EPI = false, bool SP2 = false>
; __device__ __forceinline__ void gemm_phase(PG8_LAS unsigned char* lds, const Gemm g, const Sched& S, const Epi& E, volatile PG8_LAS unsigned* sw = nullptr) {
;     ...
;         PG8_WAIT_V(2); PG8_BAR;
;         PG8_STAGE(PG8_SB(1, 0), cB + kstep, voffB); PG8_STAGE(PG8_SA(1, 0), cA + kstep, voffA); PG8_STAGE(PG8_SB(1, 1), cB + hstep + kstep, voffB);
;         PG8_WAIT_V(6); PG8_BAR;
;     __device__ __forceinline__ void run(f32x4 (&acc)[2][2][4][2], const pg8::Unit& u, int wr, int wc, int fr_, int fq_, int buf) const {
;     ...
;         const int gpm = pm0 + u.pm, colL = wc * 32 + 8 * fq, colg = u.pn * 256 + colL;
;         const LAS float* T = X + 2048 + buf * 1536; const LAS float* TB = T + 512;
;         {   f32x4 rs[2];
; #pragma unroll
;             for (int ai = 0; ai < 2; ++ai) { const f32x4 q = *(const LAS f32x4*)(T + 128 * ai + 64 * wr + 4 * fr);
;                 rs[ai][0] = rsqrtf(q[0] * (1.0f / D) + EPS); rs[ai][1] = rsqrtf(q[1] * (1.0f / D) + EPS); rs[ai][2] = rsqrtf(q[2] * (1.0f / D) + EPS); rs[ai][3] = rsqrtf(q[3] * (1.0f / D) + EPS); }
; #pragma unroll
;             for (int bj = 0; bj < 2; ++bj)
; #pragma unroll
;                 for (int n = 0; n < 2; ++n) { const f32x4 c2v = *(const LAS f32x4*)(T + 256 + 128 * bj + colL + 4 * n);
; #pragma unroll
;                     for (int ai = 0; ai < 2; ++ai)
; #pragma unroll
;                         for (int m = 0; m < 4; ++m) acc[ai][bj][m][n] = acc[ai][bj][m][n] * rs[ai][m] + c2v; } }
;         if (fr == 0 || fr == 15) {
;             const bool lastr = fr == 15;
;             LAS float* xb = X + (lastr ? 256 : 0) + colL;
.LBB0_526:
	s_lshl_b32 s4, s11, 5
	s_and_b32 s43, s4, 0x60
	s_lshl_b32 s42, s14, 6
	s_lshl_b32 s8, s14, 13
	s_lshl_b32 s9, s43, 7
	s_add_u32 s4, s2, 0x8000
	s_addc_u32 s5, s3, 0
	s_add_i32 m0, s15, 0x18000
	v_lshl_add_u64 v[14:15], s[4:5], 0, v[156:157]
	s_waitcnt vmcnt(2)
	s_barrier
	global_load_lds_dwordx4 v[14:15], off
	s_add_i32 m0, s15, 0x1a000
	v_lshl_add_u64 v[14:15], s[4:5], 0, v[160:161]
	s_add_u32 s4, s0, 0x8000
	s_addc_u32 s5, s1, 0
	s_add_i32 s53, s15, 0x8000
	global_load_lds_dwordx4 v[14:15], off
	v_lshl_add_u64 v[14:15], s[4:5], 0, v[154:155]
	s_mov_b32 m0, s53
	s_add_i32 s55, s15, 0xa000
	global_load_lds_dwordx4 v[14:15], off
	v_lshl_add_u64 v[14:15], s[4:5], 0, v[158:159]
	s_add_u32 s4, s2, 0xc000
	s_mov_b32 m0, s55
	s_addc_u32 s5, s3, 0
	global_load_lds_dwordx4 v[14:15], off
	s_add_i32 m0, s15, 0x1c000
	v_lshl_add_u64 v[14:15], s[4:5], 0, v[156:157]
	global_load_lds_dwordx4 v[14:15], off
	v_lshl_add_u64 v[14:15], s[4:5], 0, v[160:161]
	s_add_i32 m0, s15, 0x1e000
	v_and_b32_e32 v1, 15, v3
	global_load_lds_dwordx4 v[14:15], off
	v_and_b32_e32 v14, 48, v3
	v_lshlrev_b32_e32 v3, 2, v3
	s_cmpk_lt_u32 s6, 0x100
	v_lshl_or_b32 v14, v1, 6, v14
	v_and_b32_e32 v3, 32, v3
	s_cselect_b64 s[28:29], -1, 0
	s_and_b32 s58, s6, 0xffffff00
	s_lshl_b32 s6, s14, 9
	v_bitop3_b32 v15, v14, s8, v3 bitop3:0xde
	s_lshl_b32 s59, s14, 11
	s_add_i32 s8, s6, 0xffffff00
	s_cmp_gt_i32 s14, 0
	v_bitop3_b32 v229, s9, v14, v3 bitop3:0xf6
	s_cselect_b32 s8, s8, 0
	s_add_i32 s9, s6, 0x200
	s_cmp_lt_i32 s14, 3
	s_cselect_b32 s9, s9, 0x700
	s_add_i32 s30, s6, 0x300
	s_cmp_gt_i32 s14, -2
	s_cselect_b32 s30, s30, 0
	s_addk_i32 s6, 0x600
	s_cmp_lt_i32 s14, 1
	s_cselect_b32 s31, s6, 0x700
	s_lshl_b32 s8, s8, 2
	s_add_i32 s65, 0, 0x20000
	s_add_i32 s68, s65, s8
	s_lshl_b32 s8, s9, 2
	v_and_b32_e32 v4, 1, v4
	s_add_i32 s6, s7, 0xffffd400
	s_add_i32 s69, s65, s8
	s_lshl_b32 s8, s30, 2
	v_add3_u32 v3, v6, v7, v8
	v_lshlrev_b32_e32 v4, 6, v4
	s_ashr_i32 s7, s6, 31
	s_add_i32 s73, s65, s8
	s_lshl_b32 s8, s31, 2
	v_lshl_or_b32 v3, v3, 7, v4
	v_and_b32_e32 v4, 1, v9
	s_add_i32 s64, s15, 0x22000
	s_add_i32 s74, s65, s8
	s_lshl_b64 s[6:7], s[6:7], 2
	v_readlane_b32 s8, v250, 18
	v_lshl_add_u32 v162, v5, 1, v3
	v_add3_u32 v3, v11, v12, v13
	v_lshlrev_b32_e32 v4, 6, v4
	s_mov_b64 s[4:5], 0xc000
	s_waitcnt vmcnt(6)
	v_readlane_b32 s9, v250, 19
	s_add_u32 s30, s8, s6
	v_lshl_or_b32 v3, v3, 7, v4
	v_lshrrev_b32_e32 v228, 4, v2
	v_lshlrev_b32_e32 v2, 2, v2
	s_addc_u32 s31, s9, s7
	v_lshl_add_u64 v[164:165], v[162:163], 0, s[4:5]
	v_lshl_add_u32 v162, v10, 1, v3
	s_add_i32 s75, 0, 0x10000
	s_add_i32 s80, 0, 0x14000
	v_lshl_add_u64 v[166:167], v[162:163], 0, s[4:5]
	v_add_u32_e32 v230, s75, v229
	v_add_u32_e32 v231, s80, v229
	v_add_u32_e32 v232, 0, v15
	v_mov_b32_e32 v233, 0x358637bd
	s_mov_b32 s81, 0x800000
	s_movk_i32 s82, 0x3f00
	v_lshlrev_b32_e32 v234, 2, v2
	v_mov_b32_e32 v235, 0x400
	s_barrier
	s_mov_b32 s99, 0
	s_branch .LBB0_529

; template <class Epi, class Sched, bool ALIGN_EPI = false, bool SP2 = false>
; __device__ __forceinline__ void gemm_phase(PG8_LAS unsigned char* lds, const Gemm g, const Sched& S, const Epi& E, volatile PG8_LAS unsigned* sw = nullptr) {
;     ...
;         if (!has_next) break;
; #pragma unroll
;         for (int a = 0; a < 2; ++a)
; #pragma unroll
;             for (int b = 0; b < 2; ++b)
; #pragma unroll
;                 for (int m = 0; m < 4; ++m)
; #pragma unroll
;                     for (int n = 0; n < 2; ++n) acc[a][b][m][n] = (f32x4){0.f, 0.f, 0.f, 0.f};
;         cur = nxt; cA = nA; cB = nB; ++ui;
.LBB0_528:
	s_and_b64 vcc, exec, s[0:1]
	s_mov_b32 s52, s38
	s_mov_b32 s54, s36
	s_mov_b64 s[2:3], s[48:49]
	s_mov_b64 s[0:1], s[46:47]
	s_mov_b32 s56, s83
	s_cbranch_vccnz .LBB0_561
	s_mov_b32 s99, 1

; #define PG8_STAGE(bufoff, gbase, voff) do { _Pragma("unroll") for (int _i = 0; _i < 2; ++_i) \
;         __builtin_amdgcn_global_load_lds((const unsigned*)((const char*)(gbase) + (voff)[_i]), (PG8_LAS unsigned*)(lds + (bufoff) + ldsw + _i * 8192), 16, 0, 0); } while (0)
; #define PG8_LDA(dst, b, h) do { _Pragma("unroll") for (int m = 0; m < 4; ++m) _Pragma("unroll") for (int k = 0; k < 2; ++k) dst[m][k] = *(const PG8_LAS bf16x8*)(lds + PG8_SA(b, h) + aoff + m * 2048 + k * 1024); } while (0)
; #define PG8_LDB(dst, b, h) do { _Pragma("unroll") for (int n = 0; n < 2; ++n) _Pragma("unroll") for (int k = 0; k < 2; ++k) dst[n][k] = *(const PG8_LAS bf16x8*)(lds + PG8_SB(b, h) + boff + n * 2048 + k * 1024); } while (0)
; #define PG8_MMA(ai, bj, At, Bt) do { __builtin_amdgcn_s_setprio(1); _Pragma("unroll") for (int m = 0; m < 4; ++m) _Pragma("unroll") for (int n = 0; n < 2; ++n) _Pragma("unroll") for (int k = 0; k < 2; ++k) \
;         acc[ai][bj][m][n] = __builtin_amdgcn_mfma_f32_16x16x32_bf16(Bt[n][k], At[m][k], acc[ai][bj][m][n], 0, 0, 0); __builtin_amdgcn_s_setprio(0); } while (0)
; #define PG8_WAIT_V(n) asm volatile("s_waitcnt vmcnt(" #n ")" ::: "memory")
; #define PG8_WAIT_L(n) asm volatile("s_waitcnt lgkmcnt(" #n ")" ::: "memory")
; #define PG8_BAR __builtin_amdgcn_s_barrier()
; #define PG8_SCHED __builtin_amdgcn_sched_barrier(0)
; template <class Epi, class Sched, bool ALIGN_EPI = false, bool SP2 = false>
; __device__ __forceinline__ void gemm_phase(PG8_LAS unsigned char* lds, const Gemm g, const Sched& S, const Epi& E, volatile PG8_LAS unsigned* sw = nullptr) {
;     ...
;             PG8_LDB(B0, 0, 0); PG8_LDB(B1, 0, 1); PG8_SCHED; PG8_LDA(At, 0, 0); PG8_STAGE(PG8_SA(1, 1), a1 + hstep, voffA);
;             PG8_WAIT_V(8); PG8_WAIT_L(0); PG8_BAR; PG8_MMA(0, 0, At, B0); PG8_MMA(0, 1, At, B1); PG8_BAR; PG8_SCHED;
.LBB0_532:
	ds_read_b128 v[130:133], v230
	ds_read_b128 v[134:137], v230 offset:1024
	ds_read_b128 v[138:141], v230 offset:2048
	ds_read_b128 v[142:145], v230 offset:3072
	ds_read_b128 v[146:149], v231
	ds_read_b128 v[150:153], v231 offset:1024
	ds_read_b128 v[168:171], v231 offset:2048
	ds_read_b128 v[172:175], v231 offset:3072
	s_add_u32 s2, s0, 0x10000
	s_addc_u32 s3, s1, 0
	s_cmp_eq_u32 s85, 12
	s_cselect_b32 s8, s57, s2
	s_cselect_b32 s9, s37, s3
	s_cselect_b32 s6, s66, s67
	s_cselect_b32 s7, s39, s84
	s_add_u32 s4, s8, 0x8000
	s_addc_u32 s5, s9, 0
	v_lshl_add_u64 v[208:209], s[0:1], 0, v[164:165]
	s_add_i32 m0, s15, 0xc000
	ds_read_b128 v[176:179], v232
	ds_read_b128 v[180:183], v232 offset:1024
	ds_read_b128 v[184:187], v232 offset:2048
	ds_read_b128 v[188:191], v232 offset:3072
	ds_read_b128 v[192:195], v232 offset:4096
	ds_read_b128 v[196:199], v232 offset:5120
	ds_read_b128 v[200:203], v232 offset:6144
	ds_read_b128 v[204:207], v232 offset:7168
	global_load_lds_dwordx4 v[208:209], off
	v_lshl_add_u64 v[208:209], s[0:1], 0, v[166:167]
	s_add_i32 m0, s15, 0xe000
	s_nop 0
	global_load_lds_dwordx4 v[208:209], off
	s_cmp_lg_u32 s99, 0
	s_cbranch_scc1 .Lrx_p5_0_r
	s_waitcnt vmcnt(8)
	s_branch .Lrx_p5_0_j

; #define PG8_STAGE(bufoff, gbase, voff) do { _Pragma("unroll") for (int _i = 0; _i < 2; ++_i) \
;         __builtin_amdgcn_global_load_lds((const unsigned*)((const char*)(gbase) + (voff)[_i]), (PG8_LAS unsigned*)(lds + (bufoff) + ldsw + _i * 8192), 16, 0, 0); } while (0)
; #define PG8_LDA(dst, b, h) do { _Pragma("unroll") for (int m = 0; m < 4; ++m) _Pragma("unroll") for (int k = 0; k < 2; ++k) dst[m][k] = *(const PG8_LAS bf16x8*)(lds + PG8_SA(b, h) + aoff + m * 2048 + k * 1024); } while (0)
; #define PG8_MMA(ai, bj, At, Bt) do { __builtin_amdgcn_s_setprio(1); _Pragma("unroll") for (int m = 0; m < 4; ++m) _Pragma("unroll") for (int n = 0; n < 2; ++n) _Pragma("unroll") for (int k = 0; k < 2; ++k) \
;         acc[ai][bj][m][n] = __builtin_amdgcn_mfma_f32_16x16x32_bf16(Bt[n][k], At[m][k], acc[ai][bj][m][n], 0, 0, 0); __builtin_amdgcn_s_setprio(0); } while (0)
; #define PG8_WAIT_V(n) asm volatile("s_waitcnt vmcnt(" #n ")" ::: "memory")
; #define PG8_WAIT_L(n) asm volatile("s_waitcnt lgkmcnt(" #n ")" ::: "memory")
; #define PG8_BAR __builtin_amdgcn_s_barrier()
; #define PG8_SCHED __builtin_amdgcn_sched_barrier(0)
; template <class Epi, class Sched, bool ALIGN_EPI = false, bool SP2 = false>
; __device__ __forceinline__ void gemm_phase(PG8_LAS unsigned char* lds, const Gemm g, const Sched& S, const Epi& E, volatile PG8_LAS unsigned* sw = nullptr) {
;     ...
;             PG8_WAIT_V(8); PG8_WAIT_L(0); PG8_BAR; PG8_MMA(0, 0, At, B0); PG8_MMA(0, 1, At, B1); PG8_BAR; PG8_SCHED;
;             PG8_LDA(At, 0, 1); PG8_STAGE(PG8_SB(0, 0), b2, voffB); PG8_STAGE(PG8_SB(0, 1), b2 + hstep, voffB); PG8_STAGE(PG8_SA(0, 0), a2, voffA);
;             PG8_WAIT_V(8); PG8_WAIT_L(0); PG8_BAR; PG8_MMA(1, 0, At, B0); PG8_MMA(1, 1, At, B1); PG8_BAR; PG8_SCHED;
.Lrx_p5_0_j:
	s_waitcnt lgkmcnt(0)
	s_barrier
	s_setprio 1
	s_waitcnt lgkmcnt(0)
	v_mfma_f32_16x16x32_bf16 v[118:121], v[130:133], v[176:179], v[118:121]
	v_mfma_f32_16x16x32_bf16 v[122:125], v[138:141], v[176:179], v[122:125]
	v_mfma_f32_16x16x32_bf16 v[78:81], v[130:133], v[184:187], v[78:81]
	v_mfma_f32_16x16x32_bf16 v[74:77], v[138:141], v[184:187], v[74:77]
	v_mfma_f32_16x16x32_bf16 v[58:61], v[130:133], v[192:195], v[58:61]
	v_mfma_f32_16x16x32_bf16 v[54:57], v[138:141], v[192:195], v[54:57]
	v_mfma_f32_16x16x32_bf16 v[126:129], v[130:133], v[200:203], v[126:129]
	v_mfma_f32_16x16x32_bf16 v[114:117], v[138:141], v[200:203], v[114:117]
	v_mfma_f32_16x16x32_bf16 v[118:121], v[134:137], v[180:183], v[118:121]
	v_mfma_f32_16x16x32_bf16 v[122:125], v[142:145], v[180:183], v[122:125]
	v_mfma_f32_16x16x32_bf16 v[78:81], v[134:137], v[188:191], v[78:81]
	v_mfma_f32_16x16x32_bf16 v[74:77], v[142:145], v[188:191], v[74:77]
	v_mfma_f32_16x16x32_bf16 v[58:61], v[134:137], v[196:199], v[58:61]
	v_mfma_f32_16x16x32_bf16 v[54:57], v[142:145], v[196:199], v[54:57]
	v_mfma_f32_16x16x32_bf16 v[126:129], v[134:137], v[204:207], v[126:129]
	v_mfma_f32_16x16x32_bf16 v[114:117], v[142:145], v[204:207], v[114:117]
	s_setprio 0
	s_setprio 1
	v_mfma_f32_16x16x32_bf16 v[110:113], v[146:149], v[176:179], v[110:113]
	v_mfma_f32_16x16x32_bf16 v[98:101], v[168:171], v[176:179], v[98:101]
	v_mfma_f32_16x16x32_bf16 v[70:73], v[146:149], v[184:187], v[70:73]
	v_mfma_f32_16x16x32_bf16 v[66:69], v[168:171], v[184:187], v[66:69]
	v_mfma_f32_16x16x32_bf16 v[42:45], v[146:149], v[192:195], v[42:45]
	v_mfma_f32_16x16x32_bf16 v[34:37], v[168:171], v[192:195], v[34:37]
	v_mfma_f32_16x16x32_bf16 v[102:105], v[146:149], v[200:203], v[102:105]
	v_mfma_f32_16x16x32_bf16 v[90:93], v[168:171], v[200:203], v[90:93]
	v_mfma_f32_16x16x32_bf16 v[110:113], v[150:153], v[180:183], v[110:113]
	v_mfma_f32_16x16x32_bf16 v[98:101], v[172:175], v[180:183], v[98:101]
	v_mfma_f32_16x16x32_bf16 v[70:73], v[150:153], v[188:191], v[70:73]
	v_mfma_f32_16x16x32_bf16 v[66:69], v[172:175], v[188:191], v[66:69]
	v_mfma_f32_16x16x32_bf16 v[42:45], v[150:153], v[196:199], v[42:45]
	v_mfma_f32_16x16x32_bf16 v[34:37], v[172:175], v[196:199], v[34:37]
	v_mfma_f32_16x16x32_bf16 v[102:105], v[150:153], v[204:207], v[102:105]
	v_mfma_f32_16x16x32_bf16 v[90:93], v[172:175], v[204:207], v[90:93]
	s_setprio 0
	s_barrier
	s_add_i32 s0, s75, s13
	v_lshl_add_u64 v[208:209], s[6:7], 0, v[156:157]
	s_mov_b32 m0, s0
	ds_read_b128 v[176:179], v232 offset:16384
	ds_read_b128 v[180:183], v232 offset:17408
	ds_read_b128 v[184:187], v232 offset:18432
	ds_read_b128 v[188:191], v232 offset:19456
	ds_read_b128 v[192:195], v232 offset:20480
	ds_read_b128 v[196:199], v232 offset:21504
	ds_read_b128 v[200:203], v232 offset:22528
	ds_read_b128 v[204:207], v232 offset:23552
	global_load_lds_dwordx4 v[208:209], off
	s_add_i32 m0, s0, 0x2000
	s_add_u32 s0, s6, 0x4000
	v_lshl_add_u64 v[208:209], s[6:7], 0, v[160:161]
	s_addc_u32 s1, s7, 0
	s_add_i32 s86, s80, s13
	global_load_lds_dwordx4 v[208:209], off
	v_lshl_add_u64 v[208:209], s[0:1], 0, v[156:157]
	s_mov_b32 m0, s86
	s_nop 0
	global_load_lds_dwordx4 v[208:209], off
	v_lshl_add_u64 v[208:209], s[0:1], 0, v[160:161]
	s_add_i32 m0, s86, 0x2000
	s_nop 0
	global_load_lds_dwordx4 v[208:209], off
	v_lshl_add_u64 v[208:209], s[8:9], 0, v[154:155]
	s_mov_b32 m0, s15
	s_nop 0
	global_load_lds_dwordx4 v[208:209], off
	v_lshl_add_u64 v[208:209], s[8:9], 0, v[158:159]
	s_mov_b32 m0, s33
	s_nop 0
	global_load_lds_dwordx4 v[208:209], off
	s_cmp_lg_u32 s99, 0
	s_cbranch_scc1 .Lrx_p5_1_r
	s_waitcnt vmcnt(8)
	s_branch .Lrx_p5_1_j

; #define PG8_STAGE(bufoff, gbase, voff) do { _Pragma("unroll") for (int _i = 0; _i < 2; ++_i) \
;         __builtin_amdgcn_global_load_lds((const unsigned*)((const char*)(gbase) + (voff)[_i]), (PG8_LAS unsigned*)(lds + (bufoff) + ldsw + _i * 8192), 16, 0, 0); } while (0)
; #define PG8_LDA(dst, b, h) do { _Pragma("unroll") for (int m = 0; m < 4; ++m) _Pragma("unroll") for (int k = 0; k < 2; ++k) dst[m][k] = *(const PG8_LAS bf16x8*)(lds + PG8_SA(b, h) + aoff + m * 2048 + k * 1024); } while (0)
; #define PG8_LDB(dst, b, h) do { _Pragma("unroll") for (int n = 0; n < 2; ++n) _Pragma("unroll") for (int k = 0; k < 2; ++k) dst[n][k] = *(const PG8_LAS bf16x8*)(lds + PG8_SB(b, h) + boff + n * 2048 + k * 1024); } while (0)
; #define PG8_MMA(ai, bj, At, Bt) do { __builtin_amdgcn_s_setprio(1); _Pragma("unroll") for (int m = 0; m < 4; ++m) _Pragma("unroll") for (int n = 0; n < 2; ++n) _Pragma("unroll") for (int k = 0; k < 2; ++k) \
;         acc[ai][bj][m][n] = __builtin_amdgcn_mfma_f32_16x16x32_bf16(Bt[n][k], At[m][k], acc[ai][bj][m][n], 0, 0, 0); __builtin_amdgcn_s_setprio(0); } while (0)
; #define PG8_WAIT_V(n) asm volatile("s_waitcnt vmcnt(" #n ")" ::: "memory")
; #define PG8_WAIT_L(n) asm volatile("s_waitcnt lgkmcnt(" #n ")" ::: "memory")
; #define PG8_BAR __builtin_amdgcn_s_barrier()
; #define PG8_SCHED __builtin_amdgcn_sched_barrier(0)
; template <class Epi, class Sched, bool ALIGN_EPI = false, bool SP2 = false>
; __device__ __forceinline__ void gemm_phase(PG8_LAS unsigned char* lds, const Gemm g, const Sched& S, const Epi& E, volatile PG8_LAS unsigned* sw = nullptr) {
;     ...
;             PG8_WAIT_V(8); PG8_WAIT_L(0); PG8_BAR; PG8_MMA(1, 0, At, B0); PG8_MMA(1, 1, At, B1); PG8_BAR; PG8_SCHED;
;             PG8_LDB(B0, 1, 0); PG8_LDB(B1, 1, 1); PG8_SCHED; PG8_LDA(At, 1, 0); PG8_STAGE(PG8_SA(0, 1), a2 + hstep, voffA);
;             PG8_WAIT_V(8); PG8_WAIT_L(0); PG8_BAR; PG8_MMA(0, 0, At, B0); PG8_MMA(0, 1, At, B1); PG8_BAR; PG8_SCHED;
.Lrx_p5_1_j:
	s_mov_b32 s99, 0
	s_waitcnt lgkmcnt(0)
	s_barrier
	s_setprio 1
	s_waitcnt lgkmcnt(0)
	v_mfma_f32_16x16x32_bf16 v[94:97], v[130:133], v[176:179], v[94:97]
	v_mfma_f32_16x16x32_bf16 v[106:109], v[138:141], v[176:179], v[106:109]
	v_mfma_f32_16x16x32_bf16 v[38:41], v[130:133], v[184:187], v[38:41]
	v_mfma_f32_16x16x32_bf16 v[26:29], v[138:141], v[184:187], v[26:29]
	v_mfma_f32_16x16x32_bf16 v[46:49], v[130:133], v[192:195], v[46:49]
	v_mfma_f32_16x16x32_bf16 v[62:65], v[138:141], v[192:195], v[62:65]
	v_mfma_f32_16x16x32_bf16 v[2:5], v[130:133], v[200:203], v[2:5]
	v_mfma_f32_16x16x32_bf16 v[18:21], v[138:141], v[200:203], v[18:21]
	v_mfma_f32_16x16x32_bf16 v[94:97], v[134:137], v[180:183], v[94:97]
	v_mfma_f32_16x16x32_bf16 v[106:109], v[142:145], v[180:183], v[106:109]
	v_mfma_f32_16x16x32_bf16 v[38:41], v[134:137], v[188:191], v[38:41]
	v_mfma_f32_16x16x32_bf16 v[26:29], v[142:145], v[188:191], v[26:29]
	v_mfma_f32_16x16x32_bf16 v[46:49], v[134:137], v[196:199], v[46:49]
	v_mfma_f32_16x16x32_bf16 v[62:65], v[142:145], v[196:199], v[62:65]
	v_mfma_f32_16x16x32_bf16 v[2:5], v[134:137], v[204:207], v[2:5]
	v_mfma_f32_16x16x32_bf16 v[18:21], v[142:145], v[204:207], v[18:21]
	s_setprio 0
	s_setprio 1
	v_mfma_f32_16x16x32_bf16 v[86:89], v[146:149], v[176:179], v[86:89]
	v_mfma_f32_16x16x32_bf16 v[82:85], v[168:171], v[176:179], v[82:85]
	v_mfma_f32_16x16x32_bf16 v[14:17], v[146:149], v[184:187], v[14:17]
	v_mfma_f32_16x16x32_bf16 v[10:13], v[168:171], v[184:187], v[10:13]
	v_mfma_f32_16x16x32_bf16 v[30:33], v[146:149], v[192:195], v[30:33]
	v_mfma_f32_16x16x32_bf16 v[50:53], v[168:171], v[192:195], v[50:53]
	v_mfma_f32_16x16x32_bf16 v[6:9], v[146:149], v[200:203], v[6:9]
	v_mfma_f32_16x16x32_bf16 v[22:25], v[168:171], v[200:203], v[22:25]
	v_mfma_f32_16x16x32_bf16 v[86:89], v[150:153], v[180:183], v[86:89]
	v_mfma_f32_16x16x32_bf16 v[82:85], v[172:175], v[180:183], v[82:85]
	v_mfma_f32_16x16x32_bf16 v[14:17], v[150:153], v[188:191], v[14:17]
	v_mfma_f32_16x16x32_bf16 v[10:13], v[172:175], v[188:191], v[10:13]
	v_mfma_f32_16x16x32_bf16 v[30:33], v[150:153], v[196:199], v[30:33]
	v_mfma_f32_16x16x32_bf16 v[50:53], v[172:175], v[196:199], v[50:53]
	v_mfma_f32_16x16x32_bf16 v[6:9], v[150:153], v[204:207], v[6:9]
	v_mfma_f32_16x16x32_bf16 v[22:25], v[172:175], v[204:207], v[22:25]
	s_setprio 0
	s_barrier
	s_add_i32 s86, 0, 0x18000
	s_add_i32 s87, 0, 0x1c000
	v_add_u32_e32 v142, s86, v229
	v_add_u32_e32 v162, s87, v229
	ds_read_b128 v[130:133], v142
	ds_read_b128 v[134:137], v142 offset:1024
	ds_read_b128 v[138:141], v142 offset:2048
	ds_read_b128 v[142:145], v142 offset:3072
	ds_read_b128 v[146:149], v162
	ds_read_b128 v[150:153], v162 offset:1024
	ds_read_b128 v[168:171], v162 offset:2048
	ds_read_b128 v[172:175], v162 offset:3072
	s_add_u32 s0, s8, 0x4000
	s_addc_u32 s1, s9, 0
	s_mov_b32 m0, s40
	v_lshl_add_u64 v[208:209], s[0:1], 0, v[154:155]
	ds_read_b128 v[176:179], v232 offset:32768
	ds_read_b128 v[180:183], v232 offset:33792
	ds_read_b128 v[184:187], v232 offset:34816
	ds_read_b128 v[188:191], v232 offset:35840
	ds_read_b128 v[192:195], v232 offset:36864
	ds_read_b128 v[196:199], v232 offset:37888
	ds_read_b128 v[200:203], v232 offset:38912
	ds_read_b128 v[204:207], v232 offset:39936
	global_load_lds_dwordx4 v[208:209], off
	v_lshl_add_u64 v[208:209], s[0:1], 0, v[158:159]
	s_mov_b32 m0, s41
	s_nop 0
	global_load_lds_dwordx4 v[208:209], off
	s_waitcnt vmcnt(8)
	s_waitcnt lgkmcnt(0)
	s_barrier
	s_setprio 1
	s_waitcnt lgkmcnt(0)
	v_mfma_f32_16x16x32_bf16 v[118:121], v[130:133], v[176:179], v[118:121]
	v_mfma_f32_16x16x32_bf16 v[122:125], v[138:141], v[176:179], v[122:125]
	v_mfma_f32_16x16x32_bf16 v[78:81], v[130:133], v[184:187], v[78:81]
	v_mfma_f32_16x16x32_bf16 v[74:77], v[138:141], v[184:187], v[74:77]
	v_mfma_f32_16x16x32_bf16 v[58:61], v[130:133], v[192:195], v[58:61]
	v_mfma_f32_16x16x32_bf16 v[54:57], v[138:141], v[192:195], v[54:57]
	v_mfma_f32_16x16x32_bf16 v[126:129], v[130:133], v[200:203], v[126:129]
	v_mfma_f32_16x16x32_bf16 v[114:117], v[138:141], v[200:203], v[114:117]
	v_mfma_f32_16x16x32_bf16 v[118:121], v[134:137], v[180:183], v[118:121]
	v_mfma_f32_16x16x32_bf16 v[122:125], v[142:145], v[180:183], v[122:125]
	v_mfma_f32_16x16x32_bf16 v[78:81], v[134:137], v[188:191], v[78:81]
	v_mfma_f32_16x16x32_bf16 v[74:77], v[142:145], v[188:191], v[74:77]
	v_mfma_f32_16x16x32_bf16 v[58:61], v[134:137], v[196:199], v[58:61]
	v_mfma_f32_16x16x32_bf16 v[54:57], v[142:145], v[196:199], v[54:57]
	v_mfma_f32_16x16x32_bf16 v[126:129], v[134:137], v[204:207], v[126:129]
	v_mfma_f32_16x16x32_bf16 v[114:117], v[142:145], v[204:207], v[114:117]
	s_setprio 0
	s_setprio 1
	v_mfma_f32_16x16x32_bf16 v[110:113], v[146:149], v[176:179], v[110:113]
	v_mfma_f32_16x16x32_bf16 v[98:101], v[168:171], v[176:179], v[98:101]
	v_mfma_f32_16x16x32_bf16 v[70:73], v[146:149], v[184:187], v[70:73]
	v_mfma_f32_16x16x32_bf16 v[66:69], v[168:171], v[184:187], v[66:69]
	v_mfma_f32_16x16x32_bf16 v[42:45], v[146:149], v[192:195], v[42:45]
	v_mfma_f32_16x16x32_bf16 v[34:37], v[168:171], v[192:195], v[34:37]
	v_mfma_f32_16x16x32_bf16 v[102:105], v[146:149], v[200:203], v[102:105]
	v_mfma_f32_16x16x32_bf16 v[90:93], v[168:171], v[200:203], v[90:93]
	v_mfma_f32_16x16x32_bf16 v[110:113], v[150:153], v[180:183], v[110:113]
	v_mfma_f32_16x16x32_bf16 v[98:101], v[172:175], v[180:183], v[98:101]
	v_mfma_f32_16x16x32_bf16 v[70:73], v[150:153], v[188:191], v[70:73]
	v_mfma_f32_16x16x32_bf16 v[66:69], v[172:175], v[188:191], v[66:69]
	v_mfma_f32_16x16x32_bf16 v[42:45], v[150:153], v[196:199], v[42:45]
	v_mfma_f32_16x16x32_bf16 v[34:37], v[172:175], v[196:199], v[34:37]
	v_mfma_f32_16x16x32_bf16 v[102:105], v[150:153], v[204:207], v[102:105]
	v_mfma_f32_16x16x32_bf16 v[90:93], v[172:175], v[204:207], v[90:93]
	s_setprio 0
	s_barrier
; #define PG8_STAGE(bufoff, gbase, voff) do { _Pragma("unroll") for (int _i = 0; _i < 2; ++_i) \
;         __builtin_amdgcn_global_load_lds((const unsigned*)((const char*)(gbase) + (voff)[_i]), (PG8_LAS unsigned*)(lds + (bufoff) + ldsw + _i * 8192), 16, 0, 0); } while (0)
; #define PG8_LDA(dst, b, h) do { _Pragma("unroll") for (int m = 0; m < 4; ++m) _Pragma("unroll") for (int k = 0; k < 2; ++k) dst[m][k] = *(const PG8_LAS bf16x8*)(lds + PG8_SA(b, h) + aoff + m * 2048 + k * 1024); } while (0)
; #define PG8_MMA(ai, bj, At, Bt) do { __builtin_amdgcn_s_setprio(1); _Pragma("unroll") for (int m = 0; m < 4; ++m) _Pragma("unroll") for (int n = 0; n < 2; ++n) _Pragma("unroll") for (int k = 0; k < 2; ++k) \
;         acc[ai][bj][m][n] = __builtin_amdgcn_mfma_f32_16x16x32_bf16(Bt[n][k], At[m][k], acc[ai][bj][m][n], 0, 0, 0); __builtin_amdgcn_s_setprio(0); } while (0)
; #define PG8_WAIT_V(n) asm volatile("s_waitcnt vmcnt(" #n ")" ::: "memory")
; #define PG8_WAIT_L(n) asm volatile("s_waitcnt lgkmcnt(" #n ")" ::: "memory")
; #define PG8_BAR __builtin_amdgcn_s_barrier()
; #define PG8_SCHED __builtin_amdgcn_sched_barrier(0)
; template <class Epi, class Sched, bool ALIGN_EPI = false, bool SP2 = false>
; __device__ __forceinline__ void gemm_phase(PG8_LAS unsigned char* lds, const Gemm g, const Sched& S, const Epi& E, volatile PG8_LAS unsigned* sw = nullptr) {
;     ...
;             PG8_LDA(At, 1, 1); PG8_STAGE(PG8_SB(1, 0), b3, voffB); PG8_STAGE(PG8_SB(1, 1), b3 + hstep, voffB); PG8_STAGE(PG8_SA(1, 0), a3, voffA);
;             PG8_WAIT_V(8); PG8_WAIT_L(0); PG8_BAR; PG8_MMA(1, 0, At, B0); PG8_MMA(1, 1, At, B1); PG8_BAR; PG8_SCHED;
;     ...
;         if constexpr (ALIGN_EPI) { if (wr == 0) PG8_BAR; }
	s_add_u32 s0, s6, 0x8000
	s_addc_u32 s1, s7, 0
	s_add_i32 s8, s86, s13
	v_lshl_add_u64 v[208:209], s[0:1], 0, v[156:157]
	s_mov_b32 m0, s8
	ds_read_b128 v[176:179], v232 offset:49152
	ds_read_b128 v[180:183], v232 offset:50176
	ds_read_b128 v[184:187], v232 offset:51200
	ds_read_b128 v[188:191], v232 offset:52224
	ds_read_b128 v[192:195], v232 offset:53248
	ds_read_b128 v[196:199], v232 offset:54272
	ds_read_b128 v[200:203], v232 offset:55296
	ds_read_b128 v[204:207], v232 offset:56320
	global_load_lds_dwordx4 v[208:209], off
	s_add_i32 m0, s8, 0x2000
	v_lshl_add_u64 v[208:209], s[0:1], 0, v[160:161]
	s_add_u32 s0, s6, 0xc000
	s_addc_u32 s1, s7, 0
	s_add_i32 s6, s87, s13
	global_load_lds_dwordx4 v[208:209], off
	v_lshl_add_u64 v[208:209], s[0:1], 0, v[156:157]
	s_mov_b32 m0, s6
	s_nop 0
	global_load_lds_dwordx4 v[208:209], off
	v_lshl_add_u64 v[208:209], s[0:1], 0, v[160:161]
	s_add_i32 m0, s6, 0x2000
	s_nop 0
	global_load_lds_dwordx4 v[208:209], off
	v_lshl_add_u64 v[208:209], s[4:5], 0, v[154:155]
	s_mov_b32 m0, s53
	s_nop 0
	global_load_lds_dwordx4 v[208:209], off
	v_lshl_add_u64 v[208:209], s[4:5], 0, v[158:159]
	s_mov_b32 m0, s55
	s_nop 0
	global_load_lds_dwordx4 v[208:209], off
	s_waitcnt vmcnt(8)
	s_waitcnt lgkmcnt(0)
	s_barrier
	s_setprio 1
	s_waitcnt lgkmcnt(0)
	v_mfma_f32_16x16x32_bf16 v[94:97], v[130:133], v[176:179], v[94:97]
	v_mfma_f32_16x16x32_bf16 v[106:109], v[138:141], v[176:179], v[106:109]
	v_mfma_f32_16x16x32_bf16 v[38:41], v[130:133], v[184:187], v[38:41]
	v_mfma_f32_16x16x32_bf16 v[26:29], v[138:141], v[184:187], v[26:29]
	v_mfma_f32_16x16x32_bf16 v[46:49], v[130:133], v[192:195], v[46:49]
	v_mfma_f32_16x16x32_bf16 v[62:65], v[138:141], v[192:195], v[62:65]
	v_mfma_f32_16x16x32_bf16 v[2:5], v[130:133], v[200:203], v[2:5]
	v_mfma_f32_16x16x32_bf16 v[18:21], v[138:141], v[200:203], v[18:21]
	v_mfma_f32_16x16x32_bf16 v[94:97], v[134:137], v[180:183], v[94:97]
	v_mfma_f32_16x16x32_bf16 v[106:109], v[142:145], v[180:183], v[106:109]
	v_mfma_f32_16x16x32_bf16 v[38:41], v[134:137], v[188:191], v[38:41]
	v_mfma_f32_16x16x32_bf16 v[26:29], v[142:145], v[188:191], v[26:29]
	v_mfma_f32_16x16x32_bf16 v[46:49], v[134:137], v[196:199], v[46:49]
	v_mfma_f32_16x16x32_bf16 v[62:65], v[142:145], v[196:199], v[62:65]
	v_mfma_f32_16x16x32_bf16 v[2:5], v[134:137], v[204:207], v[2:5]
	v_mfma_f32_16x16x32_bf16 v[18:21], v[142:145], v[204:207], v[18:21]
	s_setprio 0
	s_setprio 1
	v_mfma_f32_16x16x32_bf16 v[86:89], v[146:149], v[176:179], v[86:89]
	v_mfma_f32_16x16x32_bf16 v[82:85], v[168:171], v[176:179], v[82:85]
	v_mfma_f32_16x16x32_bf16 v[14:17], v[146:149], v[184:187], v[14:17]
	v_mfma_f32_16x16x32_bf16 v[10:13], v[168:171], v[184:187], v[10:13]
	v_mfma_f32_16x16x32_bf16 v[30:33], v[146:149], v[192:195], v[30:33]
	v_mfma_f32_16x16x32_bf16 v[50:53], v[168:171], v[192:195], v[50:53]
	v_mfma_f32_16x16x32_bf16 v[6:9], v[146:149], v[200:203], v[6:9]
	v_mfma_f32_16x16x32_bf16 v[22:25], v[168:171], v[200:203], v[22:25]
	v_mfma_f32_16x16x32_bf16 v[86:89], v[150:153], v[180:183], v[86:89]
	v_mfma_f32_16x16x32_bf16 v[82:85], v[172:175], v[180:183], v[82:85]
	v_mfma_f32_16x16x32_bf16 v[14:17], v[150:153], v[188:191], v[14:17]
	v_mfma_f32_16x16x32_bf16 v[10:13], v[172:175], v[188:191], v[10:13]
	v_mfma_f32_16x16x32_bf16 v[30:33], v[150:153], v[196:199], v[30:33]
	v_mfma_f32_16x16x32_bf16 v[50:53], v[172:175], v[196:199], v[50:53]
	v_mfma_f32_16x16x32_bf16 v[6:9], v[150:153], v[204:207], v[6:9]
	v_mfma_f32_16x16x32_bf16 v[22:25], v[172:175], v[204:207], v[22:25]
	s_setprio 0
	s_barrier
	s_add_i32 s85, s85, 2
	s_add_u32 s67, s67, 0x10000
	s_addc_u32 s84, s84, 0
	s_cmp_gt_u32 s85, 13
	s_mov_b64 s[0:1], s[2:3]
	s_cbranch_scc0 .LBB0_532
	s_and_b64 vcc, exec, s[28:29]
	s_cbranch_vccz .LBB0_535
	s_barrier

; #define PG8_STAGE(bufoff, gbase, voff) do { _Pragma("unroll") for (int _i = 0; _i < 2; ++_i) \
;         __builtin_amdgcn_global_load_lds((const unsigned*)((const char*)(gbase) + (voff)[_i]), (PG8_LAS unsigned*)(lds + (bufoff) + ldsw + _i * 8192), 16, 0, 0); } while (0)
; #define PG8_WAIT_V(n) asm volatile("s_waitcnt vmcnt(" #n ")" ::: "memory")
; #define PG8_BAR __builtin_amdgcn_s_barrier()
; template <class Epi, class Sched, bool ALIGN_EPI = false, bool SP2 = false>
; __device__ __forceinline__ void gemm_phase(PG8_LAS unsigned char* lds, const Gemm g, const Sched& S, const Epi& E, volatile PG8_LAS unsigned* sw = nullptr) {
;     ...
;     const int tid = tid_, wid = __builtin_amdgcn_readfirstlane(tid >> 6), lane = tid & 63, wr = wid >> 2, wc = wid & 3, fr = lane & 15, fq = lane >> 4;
;     const int K = g.K, nt = K / BK;
;     unsigned voffA[2], voffB[2];
; #pragma unroll
;     for (int i = 0; i < 2; ++i) { int R, C; stage_rc(tid * 16 + i * 8192, R, C); const int Rb = Epi::PERM ? ((R & ~31) + perm32(R & 31)) : R;
;         const int Ra = Epi::PERMA ? ((R & 64) + 4 * (R & 15) + ((R >> 4) & 3)) : R;
;         voffA[i] = (unsigned)(Ra * BK + C) * 2u; voffB[i] = (unsigned)(Rb * BK + C) * 2u; }
;     const size_t kstep = (size_t)(BM * BK * 2);
;     const size_t hstep = (size_t)HALF * BK * 2;
;     const size_t tstep = (size_t)K * BM * 2;
;     const unsigned ldsw = (unsigned)wid * 1024u;
;     const int aoff = lds_byte(wr * 64 + fr, fq * 8), boff = lds_byte(wc * 32 + fr, fq * 8);
;     ...
;         PG8_WAIT_V(2); PG8_BAR;
;         PG8_STAGE(PG8_SB(1, 0), cB + kstep, voffB); PG8_STAGE(PG8_SA(1, 0), cA + kstep, voffA); PG8_STAGE(PG8_SB(1, 1), cB + hstep + kstep, voffB);
;         PG8_WAIT_V(6); PG8_BAR;
.LBB0_693:
	s_add_u32 s0, s18, 0x8000
	s_addc_u32 s1, s19, 0
	s_add_u32 s8, s14, 0x8000
	s_addc_u32 s9, s15, 0
	s_add_u32 s20, s18, 0xc000
	s_addc_u32 s21, s19, 0
	s_add_i32 m0, s25, 0x18000
	v_lshl_add_u64 v[8:9], s[0:1], 0, v[208:209]
	s_waitcnt vmcnt(2)
	s_barrier
	global_load_lds_dwordx4 v[8:9], off
	v_lshl_add_u64 v[8:9], s[0:1], 0, v[204:205]
	s_add_i32 m0, s25, 0x1a000
	s_add_i32 s34, s25, 0x8000
	global_load_lds_dwordx4 v[8:9], off
	v_lshl_add_u64 v[8:9], s[8:9], 0, v[210:211]
	s_mov_b32 m0, s34
	s_add_i32 s35, s25, 0xa000
	global_load_lds_dwordx4 v[8:9], off
	v_lshl_add_u64 v[8:9], s[8:9], 0, v[206:207]
	s_mov_b32 m0, s35
	v_bfe_u32 v219, v0, 4, 2
	global_load_lds_dwordx4 v[8:9], off
	s_add_i32 m0, s25, 0x1c000
	v_lshl_add_u64 v[8:9], s[20:21], 0, v[208:209]
	global_load_lds_dwordx4 v[8:9], off
	v_lshl_add_u64 v[8:9], s[20:21], 0, v[204:205]
	s_add_i32 m0, s25, 0x1e000
	s_and_b32 s0, s6, 3
	global_load_lds_dwordx4 v[8:9], off
	v_and_b32_e32 v218, 15, v0
	v_lshlrev_b32_e32 v7, 4, v219
	v_lshlrev_b32_e32 v0, 2, v0
	v_lshl_or_b32 v7, v218, 6, v7
	s_lshl_b32 s1, s5, 13
	v_and_b32_e32 v0, 32, v0
	s_lshl_b32 s37, s0, 5
	s_lshl_b32 s0, s0, 12
	v_bitop3_b32 v8, v7, s1, v0 bitop3:0xde
	v_bitop3_b32 v220, v7, s0, v0 bitop3:0xde
	v_lshlrev_b32_e32 v0, 10, v5
	v_and_b32_e32 v0, 0xfffff800, v0
	v_lshl_add_u32 v0, v4, 7, v0
	v_and_b32_e32 v4, 1, v5
	v_lshl_or_b32 v0, v4, 6, v0
	v_lshl_add_u32 v214, v6, 1, v0
	v_lshlrev_b32_e32 v0, 10, v1
	s_lshl_b32 s36, s5, 6
	v_and_b32_e32 v0, 0xfffff800, v0
	s_waitcnt vmcnt(6)
	s_cmpk_lt_u32 s4, 0x100
	v_lshl_add_u32 v0, v2, 7, v0
	v_and_b32_e32 v1, 1, v1
	s_cselect_b64 s[4:5], -1, 0
	v_lshl_or_b32 v0, v1, 6, v0
	s_add_i32 s40, 0, 0x10000
	s_add_i32 s41, 0, 0x14000
	s_bfe_u32 s38, s6, 0x10001
	s_and_b32 s39, s37, 32
	v_mov_b32_e32 v215, v213
	v_lshl_add_u32 v216, v3, 1, v0
	v_mov_b32_e32 v217, v213
	v_add_u32_e32 v221, s40, v220
	v_add_u32_e32 v222, s41, v220
	v_add_u32_e32 v223, 0, v8
	s_movk_i32 s42, 0x1000
	s_movk_i32 s43, 0x5000
	s_mov_b32 s44, 0x11000
	s_mov_b32 s45, 0x15000
	s_mov_b32 s46, 0x20000
	s_mov_b32 s47, 0x30000
	s_mov_b32 s48, 0x80000
	s_mov_b32 s49, 0x90000
	s_mov_b32 s50, 0xa0000
	s_mov_b32 s51, 0xb0000
	s_barrier
	s_mov_b32 s99, 0
	s_branch .LBB0_696

; template <class Epi, class Sched, bool ALIGN_EPI = false, bool SP2 = false>
; __device__ __forceinline__ void gemm_phase(PG8_LAS unsigned char* lds, const Gemm g, const Sched& S, const Epi& E, volatile PG8_LAS unsigned* sw = nullptr) {
;     ...
;         if (!has_next) break;
; #pragma unroll
;         for (int a = 0; a < 2; ++a)
; #pragma unroll
;             for (int b = 0; b < 2; ++b)
; #pragma unroll
;                 for (int m = 0; m < 4; ++m)
; #pragma unroll
;                     for (int n = 0; n < 2; ++n) acc[a][b][m][n] = (f32x4){0.f, 0.f, 0.f, 0.f};
;         cur = nxt; cA = nA; cB = nB; ++ui;
.LBB0_695:
	s_andn2_b64 vcc, exec, s[0:1]
	s_mov_b32 s10, s52
	s_mov_b32 s12, s53
	s_mov_b64 s[18:19], s[8:9]
	s_mov_b64 s[14:15], s[6:7]
	s_cbranch_vccz .LBB0_709
	s_mov_b32 s99, 1

; #define PG8_STAGE(bufoff, gbase, voff) do { _Pragma("unroll") for (int _i = 0; _i < 2; ++_i) \
;         __builtin_amdgcn_global_load_lds((const unsigned*)((const char*)(gbase) + (voff)[_i]), (PG8_LAS unsigned*)(lds + (bufoff) + ldsw + _i * 8192), 16, 0, 0); } while (0)
; #define PG8_LDA(dst, b, h) do { _Pragma("unroll") for (int m = 0; m < 4; ++m) _Pragma("unroll") for (int k = 0; k < 2; ++k) dst[m][k] = *(const PG8_LAS bf16x8*)(lds + PG8_SA(b, h) + aoff + m * 2048 + k * 1024); } while (0)
; #define PG8_LDB(dst, b, h) do { _Pragma("unroll") for (int n = 0; n < 2; ++n) _Pragma("unroll") for (int k = 0; k < 2; ++k) dst[n][k] = *(const PG8_LAS bf16x8*)(lds + PG8_SB(b, h) + boff + n * 2048 + k * 1024); } while (0)
; #define PG8_MMA(ai, bj, At, Bt) do { __builtin_amdgcn_s_setprio(1); _Pragma("unroll") for (int m = 0; m < 4; ++m) _Pragma("unroll") for (int n = 0; n < 2; ++n) _Pragma("unroll") for (int k = 0; k < 2; ++k) \
;         acc[ai][bj][m][n] = __builtin_amdgcn_mfma_f32_16x16x32_bf16(Bt[n][k], At[m][k], acc[ai][bj][m][n], 0, 0, 0); __builtin_amdgcn_s_setprio(0); } while (0)
; #define PG8_WAIT_V(n) asm volatile("s_waitcnt vmcnt(" #n ")" ::: "memory")
; #define PG8_WAIT_L(n) asm volatile("s_waitcnt lgkmcnt(" #n ")" ::: "memory")
; #define PG8_BAR __builtin_amdgcn_s_barrier()
; #define PG8_SCHED __builtin_amdgcn_sched_barrier(0)
; template <class Epi, class Sched, bool ALIGN_EPI = false, bool SP2 = false>
; __device__ __forceinline__ void gemm_phase(PG8_LAS unsigned char* lds, const Gemm g, const Sched& S, const Epi& E, volatile PG8_LAS unsigned* sw = nullptr) {
;     ...
;             PG8_LDB(B0, 0, 0); PG8_LDB(B1, 0, 1); PG8_SCHED; PG8_LDA(At, 0, 0); PG8_STAGE(PG8_SA(1, 1), a1 + hstep, voffA);
;             PG8_WAIT_V(8); PG8_WAIT_L(0); PG8_BAR; PG8_MMA(0, 0, At, B0); PG8_MMA(0, 1, At, B1); PG8_BAR; PG8_SCHED;
.LBB0_703:
	ds_read_b128 v[128:131], v221
	ds_read_b128 v[132:135], v221 offset:1024
	ds_read_b128 v[136:139], v221 offset:2048
	ds_read_b128 v[140:143], v221 offset:3072
	ds_read_b128 v[144:147], v222
	ds_read_b128 v[148:151], v222 offset:1024
	ds_read_b128 v[152:155], v222 offset:2048
	ds_read_b128 v[156:159], v222 offset:3072
	s_add_u32 s18, s14, 0x4000
	s_addc_u32 s19, s15, 0
	s_cmp_eq_u32 s54, 40
	s_cselect_b32 s22, s6, s18
	s_cselect_b32 s23, s7, s19
	s_cselect_b32 s20, s8, s11
	s_cselect_b32 s21, s9, s13
	s_add_u32 s18, s22, 0x8000
	s_addc_u32 s19, s23, 0
	v_lshl_add_u64 v[192:193], s[14:15], 0, v[214:215]
	s_add_i32 m0, s25, 0xc000
	ds_read_b128 v[160:163], v223
	ds_read_b128 v[164:167], v223 offset:1024
	ds_read_b128 v[168:171], v223 offset:2048
	ds_read_b128 v[172:175], v223 offset:3072
	ds_read_b128 v[176:179], v223 offset:4096
	ds_read_b128 v[180:183], v223 offset:5120
	ds_read_b128 v[184:187], v223 offset:6144
	ds_read_b128 v[188:191], v223 offset:7168
	global_load_lds_dwordx4 v[192:193], off
	v_lshl_add_u64 v[192:193], s[14:15], 0, v[216:217]
	s_add_i32 m0, s25, 0xe000
	s_nop 0
	global_load_lds_dwordx4 v[192:193], off
	s_cmp_lg_u32 s99, 0
	s_cbranch_scc1 .Lrx_p7_0_r
	s_waitcnt vmcnt(8)
	s_branch .Lrx_p7_0_j

; #define PG8_STAGE(bufoff, gbase, voff) do { _Pragma("unroll") for (int _i = 0; _i < 2; ++_i) \
;         __builtin_amdgcn_global_load_lds((const unsigned*)((const char*)(gbase) + (voff)[_i]), (PG8_LAS unsigned*)(lds + (bufoff) + ldsw + _i * 8192), 16, 0, 0); } while (0)
; #define PG8_LDA(dst, b, h) do { _Pragma("unroll") for (int m = 0; m < 4; ++m) _Pragma("unroll") for (int k = 0; k < 2; ++k) dst[m][k] = *(const PG8_LAS bf16x8*)(lds + PG8_SA(b, h) + aoff + m * 2048 + k * 1024); } while (0)
; #define PG8_MMA(ai, bj, At, Bt) do { __builtin_amdgcn_s_setprio(1); _Pragma("unroll") for (int m = 0; m < 4; ++m) _Pragma("unroll") for (int n = 0; n < 2; ++n) _Pragma("unroll") for (int k = 0; k < 2; ++k) \
;         acc[ai][bj][m][n] = __builtin_amdgcn_mfma_f32_16x16x32_bf16(Bt[n][k], At[m][k], acc[ai][bj][m][n], 0, 0, 0); __builtin_amdgcn_s_setprio(0); } while (0)
; #define PG8_WAIT_V(n) asm volatile("s_waitcnt vmcnt(" #n ")" ::: "memory")
; #define PG8_WAIT_L(n) asm volatile("s_waitcnt lgkmcnt(" #n ")" ::: "memory")
; #define PG8_BAR __builtin_amdgcn_s_barrier()
; #define PG8_SCHED __builtin_amdgcn_sched_barrier(0)
; template <class Epi, class Sched, bool ALIGN_EPI = false, bool SP2 = false>
; __device__ __forceinline__ void gemm_phase(PG8_LAS unsigned char* lds, const Gemm g, const Sched& S, const Epi& E, volatile PG8_LAS unsigned* sw = nullptr) {
;     ...
;             PG8_WAIT_V(8); PG8_WAIT_L(0); PG8_BAR; PG8_MMA(0, 0, At, B0); PG8_MMA(0, 1, At, B1); PG8_BAR; PG8_SCHED;
;             PG8_LDA(At, 0, 1); PG8_STAGE(PG8_SB(0, 0), b2, voffB); PG8_STAGE(PG8_SB(0, 1), b2 + hstep, voffB); PG8_STAGE(PG8_SA(0, 0), a2, voffA);
;             PG8_WAIT_V(8); PG8_WAIT_L(0); PG8_BAR; PG8_MMA(1, 0, At, B0); PG8_MMA(1, 1, At, B1); PG8_BAR; PG8_SCHED;
.Lrx_p7_0_j:
	s_waitcnt lgkmcnt(0)
	s_barrier
	s_setprio 1
	s_waitcnt lgkmcnt(0)
	v_mfma_f32_16x16x32_bf16 v[124:127], v[128:131], v[160:163], v[124:127]
	v_mfma_f32_16x16x32_bf16 v[120:123], v[136:139], v[160:163], v[120:123]
	v_mfma_f32_16x16x32_bf16 v[116:119], v[128:131], v[168:171], v[116:119]
	v_mfma_f32_16x16x32_bf16 v[112:115], v[136:139], v[168:171], v[112:115]
	v_mfma_f32_16x16x32_bf16 v[108:111], v[128:131], v[176:179], v[108:111]
	v_mfma_f32_16x16x32_bf16 v[104:107], v[136:139], v[176:179], v[104:107]
	v_mfma_f32_16x16x32_bf16 v[100:103], v[128:131], v[184:187], v[100:103]
	v_mfma_f32_16x16x32_bf16 v[96:99], v[136:139], v[184:187], v[96:99]
	v_mfma_f32_16x16x32_bf16 v[124:127], v[132:135], v[164:167], v[124:127]
	v_mfma_f32_16x16x32_bf16 v[120:123], v[140:143], v[164:167], v[120:123]
	v_mfma_f32_16x16x32_bf16 v[116:119], v[132:135], v[172:175], v[116:119]
	v_mfma_f32_16x16x32_bf16 v[112:115], v[140:143], v[172:175], v[112:115]
	v_mfma_f32_16x16x32_bf16 v[108:111], v[132:135], v[180:183], v[108:111]
	v_mfma_f32_16x16x32_bf16 v[104:107], v[140:143], v[180:183], v[104:107]
	v_mfma_f32_16x16x32_bf16 v[100:103], v[132:135], v[188:191], v[100:103]
	v_mfma_f32_16x16x32_bf16 v[96:99], v[140:143], v[188:191], v[96:99]
	s_setprio 0
	s_setprio 1
	v_mfma_f32_16x16x32_bf16 v[68:71], v[144:147], v[160:163], v[68:71]
	v_mfma_f32_16x16x32_bf16 v[60:63], v[152:155], v[160:163], v[60:63]
	v_mfma_f32_16x16x32_bf16 v[52:55], v[144:147], v[168:171], v[52:55]
	v_mfma_f32_16x16x32_bf16 v[48:51], v[152:155], v[168:171], v[48:51]
	v_mfma_f32_16x16x32_bf16 v[44:47], v[144:147], v[176:179], v[44:47]
	v_mfma_f32_16x16x32_bf16 v[40:43], v[152:155], v[176:179], v[40:43]
	v_mfma_f32_16x16x32_bf16 v[36:39], v[144:147], v[184:187], v[36:39]
	v_mfma_f32_16x16x32_bf16 v[32:35], v[152:155], v[184:187], v[32:35]
	v_mfma_f32_16x16x32_bf16 v[68:71], v[148:151], v[164:167], v[68:71]
	v_mfma_f32_16x16x32_bf16 v[60:63], v[156:159], v[164:167], v[60:63]
	v_mfma_f32_16x16x32_bf16 v[52:55], v[148:151], v[172:175], v[52:55]
	v_mfma_f32_16x16x32_bf16 v[48:51], v[156:159], v[172:175], v[48:51]
	v_mfma_f32_16x16x32_bf16 v[44:47], v[148:151], v[180:183], v[44:47]
	v_mfma_f32_16x16x32_bf16 v[40:43], v[156:159], v[180:183], v[40:43]
	v_mfma_f32_16x16x32_bf16 v[36:39], v[148:151], v[188:191], v[36:39]
	v_mfma_f32_16x16x32_bf16 v[32:35], v[156:159], v[188:191], v[32:35]
	s_setprio 0
	s_barrier
	s_add_i32 s55, s40, s24
	v_lshl_add_u64 v[192:193], s[20:21], 0, v[208:209]
	s_mov_b32 m0, s55
	ds_read_b128 v[160:163], v223 offset:16384
	ds_read_b128 v[164:167], v223 offset:17408
	ds_read_b128 v[168:171], v223 offset:18432
	ds_read_b128 v[172:175], v223 offset:19456
	ds_read_b128 v[176:179], v223 offset:20480
	ds_read_b128 v[180:183], v223 offset:21504
	ds_read_b128 v[184:187], v223 offset:22528
	ds_read_b128 v[188:191], v223 offset:23552
	global_load_lds_dwordx4 v[192:193], off
	s_add_i32 m0, s55, 0x2000
	s_add_u32 s56, s20, 0x4000
	v_lshl_add_u64 v[192:193], s[20:21], 0, v[204:205]
	s_addc_u32 s57, s21, 0
	s_add_i32 s55, s41, s24
	global_load_lds_dwordx4 v[192:193], off
	v_lshl_add_u64 v[192:193], s[56:57], 0, v[208:209]
	s_mov_b32 m0, s55
	s_nop 0
	global_load_lds_dwordx4 v[192:193], off
	v_lshl_add_u64 v[192:193], s[56:57], 0, v[204:205]
	s_add_i32 m0, s55, 0x2000
	s_nop 0
	global_load_lds_dwordx4 v[192:193], off
	v_lshl_add_u64 v[192:193], s[22:23], 0, v[210:211]
	s_mov_b32 m0, s25
	s_nop 0
	global_load_lds_dwordx4 v[192:193], off
	v_lshl_add_u64 v[192:193], s[22:23], 0, v[206:207]
	s_mov_b32 m0, s26
	s_nop 0
	global_load_lds_dwordx4 v[192:193], off
	s_cmp_lg_u32 s99, 0
	s_cbranch_scc1 .Lrx_p7_1_r
	s_waitcnt vmcnt(8)
	s_branch .Lrx_p7_1_j

; #define PG8_STAGE(bufoff, gbase, voff) do { _Pragma("unroll") for (int _i = 0; _i < 2; ++_i) \
;         __builtin_amdgcn_global_load_lds((const unsigned*)((const char*)(gbase) + (voff)[_i]), (PG8_LAS unsigned*)(lds + (bufoff) + ldsw + _i * 8192), 16, 0, 0); } while (0)
; #define PG8_LDA(dst, b, h) do { _Pragma("unroll") for (int m = 0; m < 4; ++m) _Pragma("unroll") for (int k = 0; k < 2; ++k) dst[m][k] = *(const PG8_LAS bf16x8*)(lds + PG8_SA(b, h) + aoff + m * 2048 + k * 1024); } while (0)
; #define PG8_LDB(dst, b, h) do { _Pragma("unroll") for (int n = 0; n < 2; ++n) _Pragma("unroll") for (int k = 0; k < 2; ++k) dst[n][k] = *(const PG8_LAS bf16x8*)(lds + PG8_SB(b, h) + boff + n * 2048 + k * 1024); } while (0)
; #define PG8_MMA(ai, bj, At, Bt) do { __builtin_amdgcn_s_setprio(1); _Pragma("unroll") for (int m = 0; m < 4; ++m) _Pragma("unroll") for (int n = 0; n < 2; ++n) _Pragma("unroll") for (int k = 0; k < 2; ++k) \
;         acc[ai][bj][m][n] = __builtin_amdgcn_mfma_f32_16x16x32_bf16(Bt[n][k], At[m][k], acc[ai][bj][m][n], 0, 0, 0); __builtin_amdgcn_s_setprio(0); } while (0)
; #define PG8_WAIT_V(n) asm volatile("s_waitcnt vmcnt(" #n ")" ::: "memory")
; #define PG8_WAIT_L(n) asm volatile("s_waitcnt lgkmcnt(" #n ")" ::: "memory")
; #define PG8_BAR __builtin_amdgcn_s_barrier()
; #define PG8_SCHED __builtin_amdgcn_sched_barrier(0)
; template <class Epi, class Sched, bool ALIGN_EPI = false, bool SP2 = false>
; __device__ __forceinline__ void gemm_phase(PG8_LAS unsigned char* lds, const Gemm g, const Sched& S, const Epi& E, volatile PG8_LAS unsigned* sw = nullptr) {
;     ...
;             PG8_WAIT_V(8); PG8_WAIT_L(0); PG8_BAR; PG8_MMA(1, 0, At, B0); PG8_MMA(1, 1, At, B1); PG8_BAR; PG8_SCHED;
;             PG8_LDB(B0, 1, 0); PG8_LDB(B1, 1, 1); PG8_SCHED; PG8_LDA(At, 1, 0); PG8_STAGE(PG8_SA(0, 1), a2 + hstep, voffA);
;             PG8_WAIT_V(8); PG8_WAIT_L(0); PG8_BAR; PG8_MMA(0, 0, At, B0); PG8_MMA(0, 1, At, B1); PG8_BAR; PG8_SCHED;
.Lrx_p7_1_j:
	s_mov_b32 s99, 0
	s_waitcnt lgkmcnt(0)
	s_barrier
	s_setprio 1
	s_waitcnt lgkmcnt(0)
	v_mfma_f32_16x16x32_bf16 v[92:95], v[128:131], v[160:163], v[92:95]
	v_mfma_f32_16x16x32_bf16 v[88:91], v[136:139], v[160:163], v[88:91]
	v_mfma_f32_16x16x32_bf16 v[84:87], v[128:131], v[168:171], v[84:87]
	v_mfma_f32_16x16x32_bf16 v[80:83], v[136:139], v[168:171], v[80:83]
	v_mfma_f32_16x16x32_bf16 v[76:79], v[128:131], v[176:179], v[76:79]
	v_mfma_f32_16x16x32_bf16 v[72:75], v[136:139], v[176:179], v[72:75]
	v_mfma_f32_16x16x32_bf16 v[64:67], v[128:131], v[184:187], v[64:67]
	v_mfma_f32_16x16x32_bf16 v[56:59], v[136:139], v[184:187], v[56:59]
	v_mfma_f32_16x16x32_bf16 v[92:95], v[132:135], v[164:167], v[92:95]
	v_mfma_f32_16x16x32_bf16 v[88:91], v[140:143], v[164:167], v[88:91]
	v_mfma_f32_16x16x32_bf16 v[84:87], v[132:135], v[172:175], v[84:87]
	v_mfma_f32_16x16x32_bf16 v[80:83], v[140:143], v[172:175], v[80:83]
	v_mfma_f32_16x16x32_bf16 v[76:79], v[132:135], v[180:183], v[76:79]
	v_mfma_f32_16x16x32_bf16 v[72:75], v[140:143], v[180:183], v[72:75]
	v_mfma_f32_16x16x32_bf16 v[64:67], v[132:135], v[188:191], v[64:67]
	v_mfma_f32_16x16x32_bf16 v[56:59], v[140:143], v[188:191], v[56:59]
	s_setprio 0
	s_setprio 1
	v_mfma_f32_16x16x32_bf16 v[28:31], v[144:147], v[160:163], v[28:31]
	v_mfma_f32_16x16x32_bf16 v[24:27], v[152:155], v[160:163], v[24:27]
	v_mfma_f32_16x16x32_bf16 v[20:23], v[144:147], v[168:171], v[20:23]
	v_mfma_f32_16x16x32_bf16 v[16:19], v[152:155], v[168:171], v[16:19]
	v_mfma_f32_16x16x32_bf16 v[12:15], v[144:147], v[176:179], v[12:15]
	v_mfma_f32_16x16x32_bf16 v[8:11], v[152:155], v[176:179], v[8:11]
	v_mfma_f32_16x16x32_bf16 v[4:7], v[144:147], v[184:187], v[4:7]
	v_mfma_f32_16x16x32_bf16 v[0:3], v[152:155], v[184:187], v[0:3]
	v_mfma_f32_16x16x32_bf16 v[28:31], v[148:151], v[164:167], v[28:31]
	v_mfma_f32_16x16x32_bf16 v[24:27], v[156:159], v[164:167], v[24:27]
	v_mfma_f32_16x16x32_bf16 v[20:23], v[148:151], v[172:175], v[20:23]
	v_mfma_f32_16x16x32_bf16 v[16:19], v[156:159], v[172:175], v[16:19]
	v_mfma_f32_16x16x32_bf16 v[12:15], v[148:151], v[180:183], v[12:15]
	v_mfma_f32_16x16x32_bf16 v[8:11], v[156:159], v[180:183], v[8:11]
	v_mfma_f32_16x16x32_bf16 v[4:7], v[148:151], v[188:191], v[4:7]
	v_mfma_f32_16x16x32_bf16 v[0:3], v[156:159], v[188:191], v[0:3]
	s_setprio 0
	s_barrier
	s_add_i32 s55, 0, 0x18000
	s_add_i32 s56, 0, 0x1c000
	v_add_u32_e32 v140, s55, v220
	v_add_u32_e32 v156, s56, v220
	ds_read_b128 v[128:131], v140
	ds_read_b128 v[132:135], v140 offset:1024
	ds_read_b128 v[136:139], v140 offset:2048
	ds_read_b128 v[140:143], v140 offset:3072
	ds_read_b128 v[144:147], v156
	ds_read_b128 v[148:151], v156 offset:1024
	ds_read_b128 v[152:155], v156 offset:2048
	ds_read_b128 v[156:159], v156 offset:3072
	s_add_u32 s22, s22, 0x4000
	s_addc_u32 s23, s23, 0
	s_mov_b32 m0, s27
	v_lshl_add_u64 v[192:193], s[22:23], 0, v[210:211]
	ds_read_b128 v[160:163], v223 offset:32768
	ds_read_b128 v[164:167], v223 offset:33792
	ds_read_b128 v[168:171], v223 offset:34816
	ds_read_b128 v[172:175], v223 offset:35840
	ds_read_b128 v[176:179], v223 offset:36864
	ds_read_b128 v[180:183], v223 offset:37888
	ds_read_b128 v[184:187], v223 offset:38912
	ds_read_b128 v[188:191], v223 offset:39936
	global_load_lds_dwordx4 v[192:193], off
	v_lshl_add_u64 v[192:193], s[22:23], 0, v[206:207]
	s_mov_b32 m0, s28
	s_nop 0
	global_load_lds_dwordx4 v[192:193], off
	s_waitcnt vmcnt(8)
	s_waitcnt lgkmcnt(0)
	s_barrier
	s_setprio 1
	s_waitcnt lgkmcnt(0)
	v_mfma_f32_16x16x32_bf16 v[124:127], v[128:131], v[160:163], v[124:127]
	v_mfma_f32_16x16x32_bf16 v[120:123], v[136:139], v[160:163], v[120:123]
	v_mfma_f32_16x16x32_bf16 v[116:119], v[128:131], v[168:171], v[116:119]
	v_mfma_f32_16x16x32_bf16 v[112:115], v[136:139], v[168:171], v[112:115]
	v_mfma_f32_16x16x32_bf16 v[108:111], v[128:131], v[176:179], v[108:111]
	v_mfma_f32_16x16x32_bf16 v[104:107], v[136:139], v[176:179], v[104:107]
	v_mfma_f32_16x16x32_bf16 v[100:103], v[128:131], v[184:187], v[100:103]
	v_mfma_f32_16x16x32_bf16 v[96:99], v[136:139], v[184:187], v[96:99]
	v_mfma_f32_16x16x32_bf16 v[124:127], v[132:135], v[164:167], v[124:127]
	v_mfma_f32_16x16x32_bf16 v[120:123], v[140:143], v[164:167], v[120:123]
	v_mfma_f32_16x16x32_bf16 v[116:119], v[132:135], v[172:175], v[116:119]
	v_mfma_f32_16x16x32_bf16 v[112:115], v[140:143], v[172:175], v[112:115]
	v_mfma_f32_16x16x32_bf16 v[108:111], v[132:135], v[180:183], v[108:111]
	v_mfma_f32_16x16x32_bf16 v[104:107], v[140:143], v[180:183], v[104:107]
	v_mfma_f32_16x16x32_bf16 v[100:103], v[132:135], v[188:191], v[100:103]
	v_mfma_f32_16x16x32_bf16 v[96:99], v[140:143], v[188:191], v[96:99]
	s_setprio 0
	s_setprio 1
	v_mfma_f32_16x16x32_bf16 v[68:71], v[144:147], v[160:163], v[68:71]
	v_mfma_f32_16x16x32_bf16 v[60:63], v[152:155], v[160:163], v[60:63]
	v_mfma_f32_16x16x32_bf16 v[52:55], v[144:147], v[168:171], v[52:55]
	v_mfma_f32_16x16x32_bf16 v[48:51], v[152:155], v[168:171], v[48:51]
	v_mfma_f32_16x16x32_bf16 v[44:47], v[144:147], v[176:179], v[44:47]
	v_mfma_f32_16x16x32_bf16 v[40:43], v[152:155], v[176:179], v[40:43]
	v_mfma_f32_16x16x32_bf16 v[36:39], v[144:147], v[184:187], v[36:39]
	v_mfma_f32_16x16x32_bf16 v[32:35], v[152:155], v[184:187], v[32:35]
	v_mfma_f32_16x16x32_bf16 v[68:71], v[148:151], v[164:167], v[68:71]
	v_mfma_f32_16x16x32_bf16 v[60:63], v[156:159], v[164:167], v[60:63]
	v_mfma_f32_16x16x32_bf16 v[52:55], v[148:151], v[172:175], v[52:55]
	v_mfma_f32_16x16x32_bf16 v[48:51], v[156:159], v[172:175], v[48:51]
	v_mfma_f32_16x16x32_bf16 v[44:47], v[148:151], v[180:183], v[44:47]
	v_mfma_f32_16x16x32_bf16 v[40:43], v[156:159], v[180:183], v[40:43]
	v_mfma_f32_16x16x32_bf16 v[36:39], v[148:151], v[188:191], v[36:39]
	v_mfma_f32_16x16x32_bf16 v[32:35], v[156:159], v[188:191], v[32:35]
	s_setprio 0
	s_barrier
; #define PG8_STAGE(bufoff, gbase, voff) do { _Pragma("unroll") for (int _i = 0; _i < 2; ++_i) \
;         __builtin_amdgcn_global_load_lds((const unsigned*)((const char*)(gbase) + (voff)[_i]), (PG8_LAS unsigned*)(lds + (bufoff) + ldsw + _i * 8192), 16, 0, 0); } while (0)
; #define PG8_LDA(dst, b, h) do { _Pragma("unroll") for (int m = 0; m < 4; ++m) _Pragma("unroll") for (int k = 0; k < 2; ++k) dst[m][k] = *(const PG8_LAS bf16x8*)(lds + PG8_SA(b, h) + aoff + m * 2048 + k * 1024); } while (0)
; #define PG8_MMA(ai, bj, At, Bt) do { __builtin_amdgcn_s_setprio(1); _Pragma("unroll") for (int m = 0; m < 4; ++m) _Pragma("unroll") for (int n = 0; n < 2; ++n) _Pragma("unroll") for (int k = 0; k < 2; ++k) \
;         acc[ai][bj][m][n] = __builtin_amdgcn_mfma_f32_16x16x32_bf16(Bt[n][k], At[m][k], acc[ai][bj][m][n], 0, 0, 0); __builtin_amdgcn_s_setprio(0); } while (0)
; #define PG8_WAIT_V(n) asm volatile("s_waitcnt vmcnt(" #n ")" ::: "memory")
; #define PG8_WAIT_L(n) asm volatile("s_waitcnt lgkmcnt(" #n ")" ::: "memory")
; #define PG8_BAR __builtin_amdgcn_s_barrier()
; #define PG8_SCHED __builtin_amdgcn_sched_barrier(0)
; template <class Epi, class Sched, bool ALIGN_EPI = false, bool SP2 = false>
; __device__ __forceinline__ void gemm_phase(PG8_LAS unsigned char* lds, const Gemm g, const Sched& S, const Epi& E, volatile PG8_LAS unsigned* sw = nullptr) {
;     ...
;             PG8_LDA(At, 1, 1); PG8_STAGE(PG8_SB(1, 0), b3, voffB); PG8_STAGE(PG8_SB(1, 1), b3 + hstep, voffB); PG8_STAGE(PG8_SA(1, 0), a3, voffA);
;             PG8_WAIT_V(8); PG8_WAIT_L(0); PG8_BAR; PG8_MMA(1, 0, At, B0); PG8_MMA(1, 1, At, B1); PG8_BAR; PG8_SCHED;
;     ...
;         if constexpr (ALIGN_EPI) { if (wr == 0) PG8_BAR; }
	s_add_u32 s22, s20, 0x8000
	s_addc_u32 s23, s21, 0
	s_add_i32 s55, s55, s24
	v_lshl_add_u64 v[192:193], s[22:23], 0, v[208:209]
	s_mov_b32 m0, s55
	ds_read_b128 v[160:163], v223 offset:49152
	ds_read_b128 v[164:167], v223 offset:50176
	ds_read_b128 v[168:171], v223 offset:51200
	ds_read_b128 v[172:175], v223 offset:52224
	ds_read_b128 v[176:179], v223 offset:53248
	ds_read_b128 v[180:183], v223 offset:54272
	ds_read_b128 v[184:187], v223 offset:55296
	ds_read_b128 v[188:191], v223 offset:56320
	global_load_lds_dwordx4 v[192:193], off
	s_add_i32 m0, s55, 0x2000
	s_add_u32 s20, s20, 0xc000
	v_lshl_add_u64 v[192:193], s[22:23], 0, v[204:205]
	s_addc_u32 s21, s21, 0
	s_add_i32 s22, s56, s24
	global_load_lds_dwordx4 v[192:193], off
	v_lshl_add_u64 v[192:193], s[20:21], 0, v[208:209]
	s_mov_b32 m0, s22
	s_nop 0
	global_load_lds_dwordx4 v[192:193], off
	v_lshl_add_u64 v[192:193], s[20:21], 0, v[204:205]
	s_add_i32 m0, s22, 0x2000
	s_nop 0
	global_load_lds_dwordx4 v[192:193], off
	v_lshl_add_u64 v[192:193], s[18:19], 0, v[210:211]
	s_mov_b32 m0, s34
	s_nop 0
	global_load_lds_dwordx4 v[192:193], off
	v_lshl_add_u64 v[192:193], s[18:19], 0, v[206:207]
	s_mov_b32 m0, s35
	s_nop 0
	global_load_lds_dwordx4 v[192:193], off
	s_waitcnt vmcnt(8)
	s_waitcnt lgkmcnt(0)
	s_barrier
	s_setprio 1
	s_waitcnt lgkmcnt(0)
	v_mfma_f32_16x16x32_bf16 v[92:95], v[128:131], v[160:163], v[92:95]
	v_mfma_f32_16x16x32_bf16 v[88:91], v[136:139], v[160:163], v[88:91]
	v_mfma_f32_16x16x32_bf16 v[84:87], v[128:131], v[168:171], v[84:87]
	v_mfma_f32_16x16x32_bf16 v[80:83], v[136:139], v[168:171], v[80:83]
	v_mfma_f32_16x16x32_bf16 v[76:79], v[128:131], v[176:179], v[76:79]
	v_mfma_f32_16x16x32_bf16 v[72:75], v[136:139], v[176:179], v[72:75]
	v_mfma_f32_16x16x32_bf16 v[64:67], v[128:131], v[184:187], v[64:67]
	v_mfma_f32_16x16x32_bf16 v[56:59], v[136:139], v[184:187], v[56:59]
	v_mfma_f32_16x16x32_bf16 v[92:95], v[132:135], v[164:167], v[92:95]
	v_mfma_f32_16x16x32_bf16 v[88:91], v[140:143], v[164:167], v[88:91]
	v_mfma_f32_16x16x32_bf16 v[84:87], v[132:135], v[172:175], v[84:87]
	v_mfma_f32_16x16x32_bf16 v[80:83], v[140:143], v[172:175], v[80:83]
	v_mfma_f32_16x16x32_bf16 v[76:79], v[132:135], v[180:183], v[76:79]
	v_mfma_f32_16x16x32_bf16 v[72:75], v[140:143], v[180:183], v[72:75]
	v_mfma_f32_16x16x32_bf16 v[64:67], v[132:135], v[188:191], v[64:67]
	v_mfma_f32_16x16x32_bf16 v[56:59], v[140:143], v[188:191], v[56:59]
	s_setprio 0
	s_setprio 1
	v_mfma_f32_16x16x32_bf16 v[28:31], v[144:147], v[160:163], v[28:31]
	v_mfma_f32_16x16x32_bf16 v[24:27], v[152:155], v[160:163], v[24:27]
	v_mfma_f32_16x16x32_bf16 v[20:23], v[144:147], v[168:171], v[20:23]
	v_mfma_f32_16x16x32_bf16 v[16:19], v[152:155], v[168:171], v[16:19]
	v_mfma_f32_16x16x32_bf16 v[12:15], v[144:147], v[176:179], v[12:15]
	v_mfma_f32_16x16x32_bf16 v[8:11], v[152:155], v[176:179], v[8:11]
	v_mfma_f32_16x16x32_bf16 v[4:7], v[144:147], v[184:187], v[4:7]
	v_mfma_f32_16x16x32_bf16 v[0:3], v[152:155], v[184:187], v[0:3]
	v_mfma_f32_16x16x32_bf16 v[28:31], v[148:151], v[164:167], v[28:31]
	v_mfma_f32_16x16x32_bf16 v[24:27], v[156:159], v[164:167], v[24:27]
	v_mfma_f32_16x16x32_bf16 v[20:23], v[148:151], v[172:175], v[20:23]
	v_mfma_f32_16x16x32_bf16 v[16:19], v[156:159], v[172:175], v[16:19]
	v_mfma_f32_16x16x32_bf16 v[12:15], v[148:151], v[180:183], v[12:15]
	v_mfma_f32_16x16x32_bf16 v[8:11], v[156:159], v[180:183], v[8:11]
	v_mfma_f32_16x16x32_bf16 v[4:7], v[148:151], v[188:191], v[4:7]
	v_mfma_f32_16x16x32_bf16 v[0:3], v[156:159], v[188:191], v[0:3]
	s_setprio 0
	s_barrier
	s_add_i32 s54, s54, 2
	s_add_u32 s14, s14, 0x10000
	s_addc_u32 s15, s15, 0
	s_add_u32 s11, s11, 0x10000
	s_addc_u32 s13, s13, 0
	s_cmp_gt_u32 s54, 41
	s_cbranch_scc0 .LBB0_703
	s_and_b64 vcc, exec, s[4:5]
	s_cbranch_vccz .LBB0_706
	s_barrier
